# attention loop v6 without the extra mid-QK barrier and without setprio (1 barrier per tile)
# speedup vs baseline: 1.0218x; 1.0035x over previous
; __device__ __forceinline__ float bflo(unsigned w) { return __uint_as_float(w << 16); }
; __device__ __forceinline__ float bfhi(unsigned w) { return __uint_as_float(w & 0xffff0000u); }
; __device__ __forceinline__ void attn_unit_fast(const bf16* __restrict__ Qb, const bf16* __restrict__ Kh, const bf16* __restrict__ Vh, bf16* __restrict__ Ob, int NT, char* lds, int t0, const float* __restrict__ qg) {
;   int tidf_ = threadIdx.x; asm volatile("" : "+v"(tidf_));
;   const int tid = tidf_, wid = tid >> 6, lane = tid & 63, r32 = lane & 31, hi = lane >> 5;
;   bf16* V_lds = (bf16*)lds; bf16* K_lds = (bf16*)(lds + 2 * SHM_V);
;   float* ws = (float*)(lds + 2 * SHM_V + 2 * SHM_K) + wid * 64; float* li_l = ws;
;   float l_reg = 0; f32x16 o[4] = {}; bf16x8 qr[8];
;   const bf16* Qw = Qb + (long)(wid * QBLK + r32) * LDQ + hi * 8;
;   {
;     float ssq = 0.f;
; #pragma unroll
;     for (int d0 = 0; d0 < 8; ++d0) { const v4u rw = *reinterpret_cast<const v4u*>(Qw + d0 * 16);
;       ssq += (bflo(rw.x) * bflo(rw.x) + bfhi(rw.x) * bfhi(rw.x)) + (bflo(rw.y) * bflo(rw.y) + bfhi(rw.y) * bfhi(rw.y));
;       ssq += (bflo(rw.z) * bflo(rw.z) + bfhi(rw.z) * bfhi(rw.z)) + (bflo(rw.w) * bflo(rw.w) + bfhi(rw.w) * bfhi(rw.w)); }
;     { auto rr = __builtin_amdgcn_permlane32_swap(__float_as_uint(ssq), __float_as_uint(ssq), false, false); ssq = __uint_as_float(rr[0]) + __uint_as_float(rr[1]); }
;     const float rsc = (SCALE * 1.4426950408889634f) / sqrtf(ssq * (1.f / 128.f) + EPS);
;     const int t = t0 + wid * QBLK + r32; const float frow = (float)(t >> 6), fcol = (float)(t & 63);
; #pragma unroll
;     for (int d0 = 0; d0 < 8; ++d0) { const v4u rw = *reinterpret_cast<const v4u*>(Qw + d0 * 16);
;       const f32x4 g0 = *reinterpret_cast<const f32x4*>(qg + 16 * d0 + 8 * hi), g1 = *reinterpret_cast<const f32x4*>(qg + 16 * d0 + 8 * hi + 4);
;       const float idx = d0 < 4 ? frow : fcol; v4u wv;
.LBB0_451:
	v_mov_b32_e32 v195, v252
	s_lshl_b64 s[0:1], s[20:21], 1
	v_ashrrev_i32_e32 v0, 1, v195
	v_bfe_u32 v193, v195, 5, 1
	v_and_b32_e32 v178, 0xffffffe0, v0
	v_bfi_b32 v2, s3, v0, v195
	v_mov_b64_e32 v[0:1], s[68:69]
	v_mad_i64_i32 v[0:1], s[4:5], v2, s53, v[0:1]
	v_lshlrev_b32_e32 v176, 4, v193
	v_lshlrev_b32_e32 v16, 2, v193
	v_and_b32_e32 v191, 31, v195
	v_lshl_add_u64 v[0:1], v[0:1], 0, v[176:177]
	v_and_b32_e32 v95, 32, v195
	v_mov_b32_e32 v2, v16
	global_load_dwordx4 v[56:59], v[0:1], off
	global_load_dwordx4 v[60:63], v[0:1], off offset:32
	global_load_dwordx4 v[64:67], v[0:1], off offset:64
	global_load_dwordx4 v[68:71], v[0:1], off offset:96
	global_load_dwordx4 v[72:75], v[0:1], off offset:128
	global_load_dwordx4 v[76:79], v[0:1], off offset:160
	global_load_dwordx4 v[80:83], v[0:1], off offset:192
	global_load_dwordx4 v[84:87], v[0:1], off offset:224
	v_or_b32_e32 v0, s85, v191
	global_load_dwordx4 v[32:35], v95, s[22:23] offset:16
	global_load_dwordx4 v[48:51], v95, s[22:23]
	v_add_u32_e32 v0, v0, v178
	v_cvt_f32_i32_e32 v2, v2
	v_ashrrev_i32_e32 v1, 6, v0
	v_or_b32_e32 v17, 1, v16
	v_cvt_f32_i32_e32 v8, v1
	v_mov_b32_e32 v1, v17
	v_and_b32_e32 v0, 63, v0
	v_cvt_f32_ubyte0_e32 v93, v0
	v_mul_f32_e32 v0, 0xbed49a78, v2
	v_cvt_f32_i32_e32 v1, v1
	v_exp_f32_e32 v0, v0
	v_or_b32_e32 v18, 2, v16
	v_or_b32_e32 v19, 3, v16
	v_mul_f32_e32 v1, 0xbed49a78, v1
	v_mul_f32_e32 v0, v0, v8
	v_exp_f32_e32 v1, v1
	v_mul_f32_e32 v2, 0.15915494, v0
	v_floor_f32_e32 v2, v2
	v_fma_f32 v0, v0, 0.15915494, -v2
	v_mov_b32_e32 v2, v18
	v_sin_f32_e32 v164, v0
	v_cos_f32_e32 v160, v0
	v_mul_f32_e32 v0, v1, v8
	v_mul_f32_e32 v1, 0.15915494, v0
	v_cvt_f32_i32_e32 v2, v2
	v_floor_f32_e32 v1, v1
	v_fma_f32 v0, v0, 0.15915494, -v1
	v_mov_b32_e32 v1, v19
	v_sin_f32_e32 v156, v0
	v_cos_f32_e32 v112, v0
	v_mul_f32_e32 v0, 0xbed49a78, v2
	v_cvt_f32_i32_e32 v1, v1
	v_exp_f32_e32 v0, v0
	v_or_b32_e32 v24, 8, v16
	global_load_dwordx4 v[36:39], v95, s[22:23] offset:80
	global_load_dwordx4 v[40:43], v95, s[22:23] offset:64
	v_mul_f32_e32 v1, 0xbed49a78, v1
	v_mul_f32_e32 v0, v0, v8
	v_exp_f32_e32 v1, v1
	v_mul_f32_e32 v2, 0.15915494, v0
	v_floor_f32_e32 v2, v2
	v_fma_f32 v0, v0, 0.15915494, -v2
	v_mov_b32_e32 v2, v24
	v_sin_f32_e32 v126, v0
	v_cos_f32_e32 v114, v0
	v_mul_f32_e32 v0, v1, v8
	v_mul_f32_e32 v1, 0.15915494, v0
	v_cvt_f32_i32_e32 v2, v2
	v_floor_f32_e32 v1, v1
	v_or_b32_e32 v25, 9, v16
	v_fma_f32 v0, v0, 0.15915494, -v1
	v_mov_b32_e32 v1, v25
	v_sin_f32_e32 v118, v0
	v_cos_f32_e32 v116, v0
	v_mul_f32_e32 v0, 0xbed49a78, v2
	v_cvt_f32_i32_e32 v1, v1
	v_exp_f32_e32 v0, v0
	v_or_b32_e32 v26, 10, v16
	v_or_b32_e32 v27, 11, v16
	v_mul_f32_e32 v1, 0xbed49a78, v1
	v_mul_f32_e32 v0, v0, v8
	v_exp_f32_e32 v1, v1
	v_mul_f32_e32 v2, 0.15915494, v0
	v_floor_f32_e32 v2, v2
	v_fma_f32 v0, v0, 0.15915494, -v2
	v_mov_b32_e32 v2, v26
	v_sin_f32_e32 v122, v0
	v_cos_f32_e32 v120, v0
	v_mul_f32_e32 v0, v1, v8
	v_mul_f32_e32 v1, 0.15915494, v0
	v_cvt_f32_i32_e32 v2, v2
	v_floor_f32_e32 v1, v1
	v_fma_f32 v0, v0, 0.15915494, -v1
	v_mov_b32_e32 v1, v27
	v_sin_f32_e32 v128, v0
	v_cos_f32_e32 v124, v0
	v_mul_f32_e32 v0, 0xbed49a78, v2
	v_cvt_f32_i32_e32 v1, v1
	v_exp_f32_e32 v0, v0
	v_or_b32_e32 v88, 16, v16
	global_load_dwordx4 v[44:47], v95, s[22:23] offset:144
	global_load_dwordx4 v[52:55], v95, s[22:23] offset:128
	v_mul_f32_e32 v1, 0xbed49a78, v1
	v_mul_f32_e32 v0, v0, v8
	v_exp_f32_e32 v1, v1
	v_mul_f32_e32 v2, 0.15915494, v0
	v_floor_f32_e32 v2, v2
	v_fma_f32 v0, v0, 0.15915494, -v2
	v_mov_b32_e32 v2, v88
	v_sin_f32_e32 v162, v0
	v_cos_f32_e32 v158, v0
	v_mul_f32_e32 v0, v1, v8
	v_mul_f32_e32 v1, 0.15915494, v0
	v_cvt_f32_i32_e32 v2, v2
	v_floor_f32_e32 v1, v1
	v_or_b32_e32 v111, 17, v16
	v_fma_f32 v0, v0, 0.15915494, -v1
	v_mov_b32_e32 v1, v111
	v_sin_f32_e32 v168, v0
	v_cos_f32_e32 v166, v0
	v_mul_f32_e32 v0, 0xbed49a78, v2
	v_cvt_f32_i32_e32 v1, v1
	v_exp_f32_e32 v0, v0
	v_or_b32_e32 v109, 18, v16
	v_or_b32_e32 v107, 19, v16
	v_mul_f32_e32 v1, 0xbed49a78, v1
	v_mul_f32_e32 v0, v0, v8
	v_exp_f32_e32 v1, v1
	v_mul_f32_e32 v2, 0.15915494, v0
	v_floor_f32_e32 v2, v2
	v_fma_f32 v0, v0, 0.15915494, -v2
	v_sin_f32_e32 v172, v0
	v_cos_f32_e32 v170, v0
	v_mul_f32_e32 v0, v1, v8
	v_mov_b32_e32 v2, v109
	v_mul_f32_e32 v1, 0.15915494, v0
	v_floor_f32_e32 v1, v1
	v_cvt_f32_i32_e32 v2, v2
	v_fma_f32 v0, v0, 0.15915494, -v1
	v_mov_b32_e32 v1, v107
	v_sin_f32_e32 v180, v0
	v_cvt_f32_i32_e32 v1, v1
	v_cos_f32_e32 v174, v0
	v_mul_f32_e32 v0, 0xbed49a78, v2
	v_exp_f32_e32 v0, v0
	v_mul_f32_e32 v1, 0xbed49a78, v1
	v_exp_f32_e32 v1, v1
	v_or_b32_e32 v99, 24, v16
	v_mul_f32_e32 v0, v0, v8
	v_mul_f32_e32 v2, 0.15915494, v0
	v_floor_f32_e32 v2, v2
	v_fma_f32 v0, v0, 0.15915494, -v2
	v_mul_f32_e32 v9, v1, v8
	v_sin_f32_e32 v186, v0
	v_cos_f32_e32 v184, v0
	v_mul_f32_e32 v0, 0.15915494, v9
	v_mov_b32_e32 v11, v99
	v_floor_f32_e32 v10, v0
	global_load_dwordx4 v[0:3], v95, s[22:23] offset:208
	global_load_dwordx4 v[4:7], v95, s[22:23] offset:192
	v_or_b32_e32 v97, 25, v16
	v_cvt_f32_i32_e32 v11, v11
	v_fma_f32 v9, v9, 0.15915494, -v10
	v_mov_b32_e32 v10, v97
	v_sin_f32_e32 v190, v9
	v_cos_f32_e32 v188, v9
	v_mul_f32_e32 v9, 0xbed49a78, v11
	v_cvt_f32_i32_e32 v10, v10
	v_exp_f32_e32 v9, v9
	v_or_b32_e32 v103, 26, v16
	v_or_b32_e32 v105, 27, v16
	v_mul_f32_e32 v10, 0xbed49a78, v10
	v_mul_f32_e32 v9, v9, v8
	v_exp_f32_e32 v10, v10
	v_mul_f32_e32 v11, 0.15915494, v9
	v_floor_f32_e32 v11, v11
	v_fma_f32 v9, v9, 0.15915494, -v11
	v_mov_b32_e32 v11, v103
	v_sin_f32_e32 v194, v9
	v_cos_f32_e32 v192, v9
	v_mul_f32_e32 v9, v10, v8
	v_mul_f32_e32 v10, 0.15915494, v9
	v_cvt_f32_i32_e32 v11, v11
	v_floor_f32_e32 v10, v10
	v_fma_f32 v9, v9, 0.15915494, -v10
	v_mov_b32_e32 v10, v105
	v_sin_f32_e32 v94, v9
	v_cos_f32_e32 v92, v9
	v_mul_f32_e32 v9, 0xbed49a78, v11
	v_cvt_f32_i32_e32 v10, v10
	v_exp_f32_e32 v9, v9
	s_waitcnt vmcnt(0)
; __device__ __forceinline__ float bflo(unsigned w) { return __uint_as_float(w << 16); }
; __device__ __forceinline__ float bfhi(unsigned w) { return __uint_as_float(w & 0xffff0000u); }
; __device__ __forceinline__ void attn_unit_fast(const bf16* __restrict__ Qb, const bf16* __restrict__ Kh, const bf16* __restrict__ Vh, bf16* __restrict__ Ob, int NT, char* lds, int t0, const float* __restrict__ qg) {
;     ...
;     float ssq = 0.f;
; #pragma unroll
;     for (int d0 = 0; d0 < 8; ++d0) { const v4u rw = *reinterpret_cast<const v4u*>(Qw + d0 * 16);
;       ssq += (bflo(rw.x) * bflo(rw.x) + bfhi(rw.x) * bfhi(rw.x)) + (bflo(rw.y) * bflo(rw.y) + bfhi(rw.y) * bfhi(rw.y));
;       ssq += (bflo(rw.z) * bflo(rw.z) + bfhi(rw.z) * bfhi(rw.z)) + (bflo(rw.w) * bflo(rw.w) + bfhi(rw.w) * bfhi(rw.w)); }
;     { auto rr = __builtin_amdgcn_permlane32_swap(__float_as_uint(ssq), __float_as_uint(ssq), false, false); ssq = __uint_as_float(rr[0]) + __uint_as_float(rr[1]); }
;     const float rsc = (SCALE * 1.4426950408889634f) / sqrtf(ssq * (1.f / 128.f) + EPS);
;     const int t = t0 + wid * QBLK + r32; const float frow = (float)(t >> 6), fcol = (float)(t & 63);
; #pragma unroll
;     for (int d0 = 0; d0 < 8; ++d0) { const v4u rw = *reinterpret_cast<const v4u*>(Qw + d0 * 16);
;       const f32x4 g0 = *reinterpret_cast<const f32x4*>(qg + 16 * d0 + 8 * hi), g1 = *reinterpret_cast<const f32x4*>(qg + 16 * d0 + 8 * hi + 4);
;       const float idx = d0 < 4 ? frow : fcol; v4u wv;
	v_and_b32_e32 v89, 0xffff0000, v87
	v_lshlrev_b32_e32 v90, 16, v86
	v_mul_f32_e32 v10, 0xbed49a78, v10
	v_mul_f32_e32 v9, v9, v8
	v_exp_f32_e32 v10, v10
	v_mul_f32_e32 v11, 0.15915494, v9
	v_floor_f32_e32 v11, v11
	v_fma_f32 v9, v9, 0.15915494, -v11
	v_sin_f32_e32 v98, v9
	v_cos_f32_e32 v96, v9
	v_mul_f32_e32 v20, v10, v8
	global_load_dwordx4 v[8:11], v95, s[22:23] offset:272
	global_load_dwordx4 v[12:15], v95, s[22:23] offset:256
	v_mul_f32_e32 v21, 0.15915494, v20
	v_cvt_f32_i32_e32 v16, v16
	v_cvt_f32_i32_e32 v17, v17
	v_floor_f32_e32 v21, v21
	v_fma_f32 v20, v20, 0.15915494, -v21
	v_mul_f32_e32 v16, 0xbed49a78, v16
	v_exp_f32_e32 v16, v16
	v_mul_f32_e32 v17, 0xbed49a78, v17
	v_exp_f32_e32 v17, v17
	v_sin_f32_e32 v102, v20
	v_mul_f32_e32 v16, v16, v93
	v_cos_f32_e32 v104, v20
	v_mul_f32_e32 v20, 0.15915494, v16
	v_floor_f32_e32 v20, v20
	v_fma_f32 v16, v16, 0.15915494, -v20
	v_sin_f32_e32 v108, v16
	v_cos_f32_e32 v106, v16
	v_mul_f32_e32 v16, v17, v93
	v_mul_f32_e32 v17, 0.15915494, v16
	v_cvt_f32_i32_e32 v18, v18
	v_floor_f32_e32 v17, v17
	v_fma_f32 v16, v16, 0.15915494, -v17
	v_sin_f32_e32 v130, v16
	v_cos_f32_e32 v132, v16
	v_mul_f32_e32 v17, 0xbed49a78, v18
	v_cvt_f32_i32_e32 v16, v19
	v_exp_f32_e32 v17, v17
	global_load_dwordx4 v[20:23], v95, s[22:23] offset:336
	global_load_dwordx4 v[28:31], v95, s[22:23] offset:320
	v_mul_f32_e32 v16, 0xbed49a78, v16
	v_exp_f32_e32 v16, v16
	v_mul_f32_e32 v17, v17, v93
	v_mul_f32_e32 v18, 0.15915494, v17
	v_floor_f32_e32 v18, v18
	v_fma_f32 v17, v17, 0.15915494, -v18
	v_mul_f32_e32 v16, v16, v93
	v_sin_f32_e32 v142, v17
	v_cos_f32_e32 v138, v17
	v_mul_f32_e32 v17, 0.15915494, v16
	v_cvt_f32_i32_e32 v18, v24
	v_floor_f32_e32 v17, v17
	v_fma_f32 v16, v16, 0.15915494, -v17
	v_sin_f32_e32 v144, v16
	v_cos_f32_e32 v146, v16
	v_mul_f32_e32 v17, 0xbed49a78, v18
	v_cvt_f32_i32_e32 v16, v25
	v_exp_f32_e32 v17, v17
	v_mul_f32_e32 v16, 0xbed49a78, v16
	v_exp_f32_e32 v16, v16
	v_mul_f32_e32 v17, v17, v93
	v_mul_f32_e32 v18, 0.15915494, v17
	v_floor_f32_e32 v18, v18
	v_fma_f32 v17, v17, 0.15915494, -v18
	v_mul_f32_e32 v16, v16, v93
	v_sin_f32_e32 v150, v17
	v_cos_f32_e32 v148, v17
	v_mul_f32_e32 v17, 0.15915494, v16
	v_cvt_f32_i32_e32 v18, v26
	v_floor_f32_e32 v17, v17
	v_fma_f32 v16, v16, 0.15915494, -v17
	v_sin_f32_e32 v110, v16
	v_cos_f32_e32 v134, v16
	v_cvt_f32_i32_e32 v16, v27
	v_mul_f32_e32 v17, 0xbed49a78, v18
	v_exp_f32_e32 v17, v17
	v_and_b32_e32 v91, 0xffff0000, v86
	v_mul_f32_e32 v16, 0xbed49a78, v16
	v_exp_f32_e32 v16, v16
	v_mul_f32_e32 v17, v17, v93
	v_mul_f32_e32 v18, 0.15915494, v17
	v_floor_f32_e32 v18, v18
	v_fma_f32 v17, v17, 0.15915494, -v18
	v_mul_f32_e32 v16, v16, v93
	v_sin_f32_e32 v140, v17
	v_cos_f32_e32 v136, v17
	v_mul_f32_e32 v17, 0.15915494, v16
	v_floor_f32_e32 v17, v17
	v_fma_f32 v113, v16, 0.15915494, -v17
	global_load_dwordx4 v[16:19], v95, s[22:23] offset:400
	global_load_dwordx4 v[24:27], v95, s[22:23] offset:384
	v_lshlrev_b32_e32 v86, 16, v85
	v_cvt_f32_i32_e32 v115, v88
	v_lshlrev_b32_e32 v88, 16, v87
	v_and_b32_e32 v87, 0xffff0000, v85
	v_and_b32_e32 v85, 0xffff0000, v83
	v_and_b32_e32 v153, 0xffff0000, v82
	v_lshlrev_b32_e32 v100, 16, v84
	v_and_b32_e32 v101, 0xffff0000, v84
	v_lshlrev_b32_e32 v84, 16, v83
	v_lshlrev_b32_e32 v152, 16, v82
	v_mov_b32_e32 v154, v153
	v_mov_b32_e32 v155, v85
	v_mov_b32_e32 v82, v152
	v_mov_b32_e32 v83, v84
	v_pk_mul_f32 v[154:155], v[154:155], v[154:155]
	v_and_b32_e32 v197, 0xffff0000, v76
	v_pk_fma_f32 v[212:213], v[82:83], v[82:83], v[154:155]
	v_lshlrev_b32_e32 v82, 16, v81
	v_and_b32_e32 v83, 0xffff0000, v81
	v_lshlrev_b32_e32 v154, 16, v80
	v_and_b32_e32 v155, 0xffff0000, v80
	v_lshlrev_b32_e32 v80, 16, v79
	v_and_b32_e32 v81, 0xffff0000, v79
	v_and_b32_e32 v79, 0xffff0000, v77
	v_lshlrev_b32_e32 v182, 16, v78
	v_and_b32_e32 v183, 0xffff0000, v78
	v_lshlrev_b32_e32 v78, 16, v77
	v_lshlrev_b32_e32 v196, 16, v76
	v_mov_b32_e32 v198, v197
	v_mov_b32_e32 v199, v79
	v_mov_b32_e32 v76, v196
	v_mov_b32_e32 v77, v78
	v_pk_mul_f32 v[198:199], v[198:199], v[198:199]
	v_and_b32_e32 v203, 0xffff0000, v70
	v_pk_fma_f32 v[214:215], v[76:77], v[76:77], v[198:199]
	v_lshlrev_b32_e32 v76, 16, v75
	v_and_b32_e32 v77, 0xffff0000, v75
	v_lshlrev_b32_e32 v198, 16, v74
	v_and_b32_e32 v199, 0xffff0000, v74
	v_lshlrev_b32_e32 v74, 16, v73
	v_and_b32_e32 v75, 0xffff0000, v73
	v_and_b32_e32 v73, 0xffff0000, v71
	v_lshlrev_b32_e32 v200, 16, v72
	v_and_b32_e32 v201, 0xffff0000, v72
	v_lshlrev_b32_e32 v72, 16, v71
	v_lshlrev_b32_e32 v202, 16, v70
	v_mov_b32_e32 v204, v203
	v_mov_b32_e32 v205, v73
	v_and_b32_e32 v245, 0xffff0000, v59
	v_and_b32_e32 v219, 0xffff0000, v58
	v_mov_b32_e32 v70, v202
	v_mov_b32_e32 v71, v72
	v_pk_mul_f32 v[204:205], v[204:205], v[204:205]
	v_lshlrev_b32_e32 v240, 16, v61
	v_and_b32_e32 v241, 0xffff0000, v61
	v_lshlrev_b32_e32 v242, 16, v60
	v_and_b32_e32 v243, 0xffff0000, v60
	v_lshlrev_b32_e32 v244, 16, v59
	v_lshlrev_b32_e32 v218, 16, v58
	v_mov_b32_e32 v60, v219
	v_mov_b32_e32 v61, v245
	v_pk_fma_f32 v[210:211], v[70:71], v[70:71], v[204:205]
	v_lshlrev_b32_e32 v70, 16, v69
	v_and_b32_e32 v71, 0xffff0000, v69
	v_lshlrev_b32_e32 v232, 16, v68
	v_and_b32_e32 v233, 0xffff0000, v68
	v_lshlrev_b32_e32 v68, 16, v67
	v_and_b32_e32 v69, 0xffff0000, v67
	v_and_b32_e32 v67, 0xffff0000, v65
	v_and_b32_e32 v237, 0xffff0000, v64
	v_mov_b32_e32 v58, v218
	v_mov_b32_e32 v59, v244
	v_pk_mul_f32 v[60:61], v[60:61], v[60:61]
	v_and_b32_e32 v221, 0xffff0000, v57
	v_and_b32_e32 v223, 0xffff0000, v56
	v_lshlrev_b32_e32 v234, 16, v66
	v_and_b32_e32 v235, 0xffff0000, v66
	v_lshlrev_b32_e32 v66, 16, v65
	v_lshlrev_b32_e32 v236, 16, v64
; __device__ __forceinline__ float bflo(unsigned w) { return __uint_as_float(w << 16); }
; __device__ __forceinline__ float bfhi(unsigned w) { return __uint_as_float(w & 0xffff0000u); }
; __device__ __forceinline__ void attn_unit_fast(const bf16* __restrict__ Qb, const bf16* __restrict__ Kh, const bf16* __restrict__ Vh, bf16* __restrict__ Ob, int NT, char* lds, int t0, const float* __restrict__ qg) {
;     ...
;     for (int d0 = 0; d0 < 8; ++d0) { const v4u rw = *reinterpret_cast<const v4u*>(Qw + d0 * 16);
;       ssq += (bflo(rw.x) * bflo(rw.x) + bfhi(rw.x) * bfhi(rw.x)) + (bflo(rw.y) * bflo(rw.y) + bfhi(rw.y) * bfhi(rw.y));
;       ssq += (bflo(rw.z) * bflo(rw.z) + bfhi(rw.z) * bfhi(rw.z)) + (bflo(rw.w) * bflo(rw.w) + bfhi(rw.w) * bfhi(rw.w)); }
;     { auto rr = __builtin_amdgcn_permlane32_swap(__float_as_uint(ssq), __float_as_uint(ssq), false, false); ssq = __uint_as_float(rr[0]) + __uint_as_float(rr[1]); }
;     const float rsc = (SCALE * 1.4426950408889634f) / sqrtf(ssq * (1.f / 128.f) + EPS);
;     const int t = t0 + wid * QBLK + r32; const float frow = (float)(t >> 6), fcol = (float)(t & 63);
	v_mov_b32_e32 v204, v237
	v_mov_b32_e32 v205, v67
	v_pk_fma_f32 v[58:59], v[58:59], v[58:59], v[60:61]
	v_lshlrev_b32_e32 v220, 16, v57
	v_lshlrev_b32_e32 v222, 16, v56
	v_mov_b32_e32 v60, v223
	v_mov_b32_e32 v61, v221
	v_mov_b32_e32 v64, v236
	v_mov_b32_e32 v65, v66
	v_pk_mul_f32 v[204:205], v[204:205], v[204:205]
	v_mov_b32_e32 v56, v222
	v_mov_b32_e32 v57, v220
	v_pk_mul_f32 v[60:61], v[60:61], v[60:61]
	v_pk_fma_f32 v[206:207], v[64:65], v[64:65], v[204:205]
	v_lshlrev_b32_e32 v64, 16, v63
	v_and_b32_e32 v65, 0xffff0000, v63
	v_lshlrev_b32_e32 v238, 16, v62
	v_and_b32_e32 v239, 0xffff0000, v62
	v_mul_f32_e32 v62, v240, v240
	v_pk_fma_f32 v[56:57], v[56:57], v[56:57], v[60:61]
	v_mul_f32_e32 v60, v242, v242
	v_pk_mul_f32 v[204:205], v[64:65], v[64:65]
	v_pk_fma_f32 v[62:63], v[240:241], v[240:241], v[62:63] op_sel_hi:[1,1,0]
	v_pk_fma_f32 v[208:209], v[242:243], v[242:243], v[60:61] op_sel_hi:[1,1,0]
	v_mov_b32_e32 v62, v205
	v_mov_b32_e32 v208, v204
	v_pk_mul_f32 v[204:205], v[238:239], v[238:239]
	v_pk_add_f32 v[58:59], v[58:59], v[58:59] op_sel_hi:[0,1]
	v_pk_add_f32 v[56:57], v[56:57], v[56:57] op_sel_hi:[0,1]
	v_mov_b32_e32 v58, v204
	v_mov_b32_e32 v56, v205
	v_pk_add_f32 v[56:57], v[58:59], v[56:57]
	v_mul_f32_e32 v58, v68, v68
	v_pk_fma_f32 v[58:59], v[68:69], v[68:69], v[58:59] op_sel_hi:[1,1,0]
	v_cvt_f32_i32_e32 v111, v111
	v_pk_add_f32 v[62:63], v[208:209], v[62:63]
	v_mul_f32_e32 v58, v234, v234
	v_pk_mul_f32 v[204:205], v[232:233], v[232:233]
	v_pk_add_f32 v[56:57], v[56:57], v[62:63]
	v_pk_fma_f32 v[62:63], v[234:235], v[234:235], v[58:59] op_sel_hi:[1,1,0]
	v_mul_f32_e32 v61, 0xbed49a78, v115
	v_mov_b32_e32 v62, v204
	v_mov_b32_e32 v58, v205
	v_exp_f32_e32 v61, v61
	v_mul_f32_e32 v111, 0xbed49a78, v111
	v_pk_add_f32 v[58:59], v[62:63], v[58:59]
	v_pk_mul_f32 v[62:63], v[70:71], v[70:71]
	v_pk_add_f32 v[206:207], v[206:207], v[206:207] op_sel_hi:[0,1]
	v_pk_add_f32 v[56:57], v[56:57], v[56:57] op_sel_hi:[0,1]
	v_exp_f32_e32 v111, v111
	v_mov_b32_e32 v206, v62
	v_mov_b32_e32 v56, v63
	v_pk_add_f32 v[56:57], v[206:207], v[56:57]
	v_mul_f32_e32 v61, v61, v93
	v_pk_add_f32 v[56:57], v[58:59], v[56:57]
	v_mul_f32_e32 v58, v200, v200
	v_pk_mul_f32 v[62:63], v[198:199], v[198:199]
	v_mul_f32_e32 v206, v74, v74
	v_pk_fma_f32 v[58:59], v[200:201], v[200:201], v[58:59] op_sel_hi:[1,1,0]
	v_sin_f32_e32 v60, v113
	v_cos_f32_e32 v204, v113
	v_mul_f32_e32 v113, 0.15915494, v61
	v_pk_fma_f32 v[216:217], v[74:75], v[74:75], v[206:207] op_sel_hi:[1,1,0]
	v_mov_b32_e32 v58, v62
	v_mul_f32_e32 v62, v111, v93
	v_floor_f32_e32 v113, v113
	v_mov_b32_e32 v216, v63
	v_mul_f32_e32 v63, 0.15915494, v62
	v_fma_f32 v61, v61, 0.15915494, -v113
	v_floor_f32_e32 v63, v63
	v_sin_f32_e32 v208, v61
	v_fma_f32 v111, v62, 0.15915494, -v63
	v_cos_f32_e32 v206, v61
	v_pk_mul_f32 v[62:63], v[76:77], v[76:77]
	v_cvt_f32_i32_e32 v61, v109
	v_pk_add_f32 v[210:211], v[210:211], v[210:211] op_sel_hi:[0,1]
	v_pk_add_f32 v[56:57], v[56:57], v[56:57] op_sel_hi:[0,1]
	v_mov_b32_e32 v210, v62
	v_mov_b32_e32 v56, v63
	v_pk_add_f32 v[58:59], v[58:59], v[216:217]
	v_pk_add_f32 v[56:57], v[210:211], v[56:57]
	v_mul_f32_e32 v210, v80, v80
	v_pk_add_f32 v[56:57], v[58:59], v[56:57]
	v_mul_f32_e32 v58, v182, v182
	v_pk_mul_f32 v[62:63], v[154:155], v[154:155]
	v_pk_fma_f32 v[216:217], v[80:81], v[80:81], v[210:211] op_sel_hi:[1,1,0]
	v_pk_fma_f32 v[58:59], v[182:183], v[182:183], v[58:59] op_sel_hi:[1,1,0]
	v_mul_f32_e32 v61, 0xbed49a78, v61
	v_mov_b32_e32 v58, v62
	v_mov_b32_e32 v216, v63
	v_exp_f32_e32 v61, v61
	v_pk_mul_f32 v[62:63], v[82:83], v[82:83]
	v_pk_add_f32 v[214:215], v[214:215], v[214:215] op_sel_hi:[0,1]
	v_pk_add_f32 v[56:57], v[56:57], v[56:57] op_sel_hi:[0,1]
	v_mov_b32_e32 v214, v62
	v_mov_b32_e32 v56, v63
	v_pk_add_f32 v[58:59], v[58:59], v[216:217]
	v_pk_add_f32 v[56:57], v[214:215], v[56:57]
	v_pk_mul_f32 v[62:63], v[90:91], v[90:91]
	v_pk_add_f32 v[56:57], v[58:59], v[56:57]
	v_mul_f32_e32 v58, v100, v100
	v_mul_f32_e32 v214, v86, v86
	v_pk_fma_f32 v[58:59], v[100:101], v[100:101], v[58:59] op_sel_hi:[1,1,0]
	v_mul_f32_e32 v61, v61, v93
	v_pk_fma_f32 v[214:215], v[86:87], v[86:87], v[214:215] op_sel_hi:[1,1,0]
	v_mov_b32_e32 v58, v62
	v_mul_f32_e32 v62, 0.15915494, v61
	v_mov_b32_e32 v214, v63
	v_floor_f32_e32 v109, v62
	v_pk_mul_f32 v[62:63], v[88:89], v[88:89]
	v_pk_add_f32 v[212:213], v[212:213], v[212:213] op_sel_hi:[0,1]
	v_pk_add_f32 v[56:57], v[56:57], v[56:57] op_sel_hi:[0,1]
	v_mov_b32_e32 v212, v62
	v_mov_b32_e32 v56, v63
	v_pk_add_f32 v[58:59], v[58:59], v[214:215]
	v_pk_add_f32 v[56:57], v[212:213], v[56:57]
	s_add_u32 s44, s16, s0
	v_pk_add_f32 v[56:57], v[58:59], v[56:57]
	v_fma_f32 v58, v61, 0.15915494, -v109
	v_pk_add_f32 v[56:57], v[56:57], v[56:57] op_sel:[0,1] op_sel_hi:[1,0]
	v_cvt_f32_i32_e32 v107, v107
	v_mov_b32_e32 v57, v56
	s_nop 1
	v_permlane32_swap_b32_e32 v56, v57
	v_add_f32_e32 v56, v56, v57
	v_fmamk_f32 v56, v56, 0x3c000000, v185
	v_mul_f32_e32 v57, 0x4f800000, v56
	v_cmp_gt_f32_e32 vcc, s89, v56
	v_mul_f32_e32 v59, 0xbed49a78, v107
	v_exp_f32_e32 v59, v59
	v_cndmask_b32_e32 v56, v56, v57, vcc
	v_sqrt_f32_e32 v57, v56
	v_sin_f32_e32 v230, v58
	v_cos_f32_e32 v228, v58
	v_mul_f32_e32 v63, v59, v93
	v_add_u32_e32 v61, -1, v57
	v_fma_f32 v62, -v61, v57, v56
	v_cmp_ge_f32_e64 s[4:5], 0, v62
	v_add_u32_e32 v62, 1, v57
	s_addc_u32 s45, s17, s1
	v_cndmask_b32_e64 v61, v57, v61, s[4:5]
	v_fma_f32 v57, -v62, v57, v56
	v_cmp_lt_f32_e64 s[4:5], 0, v57
	s_add_u32 s66, s18, s0
	s_addc_u32 s67, s19, s1
	v_cndmask_b32_e64 v57, v61, v62, s[4:5]
	v_mul_f32_e32 v61, 0x37800000, v57
	v_cndmask_b32_e32 v57, v57, v61, vcc
	v_cmp_class_f32_e32 vcc, v56, v187
; #define QROPE(RW, GA, GB, E2, OUT) do { int pp = (8 * d0 + 4 * hi + (E2)) & 31; asm volatile("" : "+v"(pp)); const float freq = __builtin_amdgcn_exp2f(-(float)pp * (13.287712379549449f / 32.f)); \
;         float sn, cs; sincos_rev(idx * freq * INV2PI, sn, cs); const float y0 = bflo(RW) * rsc * (GA), y1 = bfhi(RW) * rsc * (GB); OUT = cvtpk(y0 * cs - y1 * sn, y0 * sn + y1 * cs); } while (0)
; __device__ __forceinline__ void attn_unit_fast(const bf16* __restrict__ Qb, const bf16* __restrict__ Kh, const bf16* __restrict__ Vh, bf16* __restrict__ Ob, int NT, char* lds, int t0, const float* __restrict__ qg) {
;     ...
;     const float rsc = (SCALE * 1.4426950408889634f) / sqrtf(ssq * (1.f / 128.f) + EPS);
;     const int t = t0 + wid * QBLK + r32; const float frow = (float)(t >> 6), fcol = (float)(t & 63);
; #pragma unroll
;     for (int d0 = 0; d0 < 8; ++d0) { const v4u rw = *reinterpret_cast<const v4u*>(Qw + d0 * 16);
;       const f32x4 g0 = *reinterpret_cast<const f32x4*>(qg + 16 * d0 + 8 * hi), g1 = *reinterpret_cast<const f32x4*>(qg + 16 * d0 + 8 * hi + 4);
;       const float idx = d0 < 4 ? frow : fcol; v4u wv;
;     ...
;       QROPE(rw.x, g0.x, g0.y, 0, wv.x); QROPE(rw.y, g0.z, g0.w, 1, wv.y); QROPE(rw.z, g1.x, g1.y, 2, wv.z); QROPE(rw.w, g1.z, g1.w, 3, wv.w);
;     ...
;       qr[d0] = __builtin_bit_cast(bf16x8, wv); }
	v_sin_f32_e32 v210, v111
	v_cos_f32_e32 v216, v111
	v_cndmask_b32_e32 v56, v57, v56, vcc
	v_div_scale_f32 v57, s[4:5], v56, v56, s72
	v_rcp_f32_e32 v61, v57
	v_and_b32_e32 v179, 63, v195
	s_cmp_lg_u32 0, -1
	s_cselect_b32 s4, 0, 0
	v_fma_f32 v58, -v57, v61, 1.0
	v_fmac_f32_e32 v61, v58, v61
	v_div_scale_f32 v58, vcc, s72, v56, s72
	v_mul_f32_e32 v59, v58, v61
	v_fma_f32 v62, -v57, v59, v58
	v_fmac_f32_e32 v59, v62, v61
	v_fma_f32 v57, -v57, v59, v58
	v_div_fmas_f32 v57, v57, v61, v59
	v_div_fixup_f32 v62, v57, v56, s72
	v_pk_mul_f32 v[56:57], v[62:63], v[222:223] op_sel_hi:[0,1]
	v_pk_mul_f32 v[48:49], v[48:49], v[56:57]
	s_mov_b32 s20, 4
	v_pk_mul_f32 v[56:57], v[48:49], v[164:165] op_sel:[1,0] op_sel_hi:[0,0]
	v_pk_fma_f32 v[222:223], v[48:49], v[160:161], v[56:57] neg_lo:[0,0,1] neg_hi:[0,0,1]
	v_pk_fma_f32 v[160:161], v[48:49], v[160:161], v[56:57] op_sel_hi:[1,0,1]
	v_pk_mul_f32 v[48:49], v[62:63], v[220:221] op_sel_hi:[0,1]
	v_pk_mul_f32 v[164:165], v[50:51], v[48:49]
	global_load_dwordx4 v[48:51], v95, s[22:23] offset:464
	global_load_dwordx4 v[56:59], v95, s[22:23] offset:448
	v_mul_f32_e32 v95, 0.15915494, v63
	v_cvt_f32_i32_e32 v61, v99
	v_floor_f32_e32 v95, v95
	v_fma_f32 v63, v63, 0.15915494, -v95
	v_mul_f32_e32 v61, 0xbed49a78, v61
	v_exp_f32_e32 v61, v61
	v_cvt_f32_i32_e32 v95, v97
	v_pk_mul_f32 v[156:157], v[164:165], v[156:157] op_sel:[1,0] op_sel_hi:[0,0]
	v_pk_fma_f32 v[220:221], v[164:165], v[112:113], v[156:157] neg_lo:[0,0,1] neg_hi:[0,0,1]
	v_mul_f32_e32 v61, v61, v93
	v_pk_fma_f32 v[112:113], v[164:165], v[112:113], v[156:157] op_sel_hi:[1,0,1]
	v_sin_f32_e32 v212, v63
	v_cos_f32_e32 v164, v63
	v_mul_f32_e32 v63, 0.15915494, v61
	v_floor_f32_e32 v63, v63
	v_fma_f32 v61, v61, 0.15915494, -v63
	v_mul_f32_e32 v63, 0xbed49a78, v95
	v_exp_f32_e32 v63, v63
	v_sin_f32_e32 v214, v61
	v_cos_f32_e32 v160, v61
	v_mul_f32_e32 v61, v63, v93
	v_mul_f32_e32 v63, 0.15915494, v61
	v_floor_f32_e32 v63, v63
	v_fma_f32 v61, v61, 0.15915494, -v63
	v_cvt_f32_i32_e32 v63, v103
	v_cvt_pk_bf16_f32 v112, v222, v161
	v_sin_f32_e32 v222, v61
	v_pk_mul_f32 v[156:157], v[62:63], v[218:219] op_sel_hi:[0,1]
	v_pk_mul_f32 v[32:33], v[32:33], v[156:157]
	v_cos_f32_e32 v224, v61
	v_pk_mul_f32 v[126:127], v[32:33], v[126:127] op_sel:[1,0] op_sel_hi:[0,0]
	v_pk_fma_f32 v[156:157], v[32:33], v[114:115], v[126:127] neg_lo:[0,0,1] neg_hi:[0,0,1]
	v_pk_fma_f32 v[32:33], v[32:33], v[114:115], v[126:127] op_sel_hi:[1,0,1]
	v_cvt_pk_bf16_f32 v113, v220, v113
	v_mul_f32_e32 v32, 0xbed49a78, v63
	v_cvt_f32_i32_e32 v63, v105
	v_exp_f32_e32 v32, v32
	v_cvt_pk_bf16_f32 v114, v156, v33
	v_lshlrev_b32_e32 v33, 3, v195
	v_mul_f32_e32 v63, 0xbed49a78, v63
	v_exp_f32_e32 v63, v63
	v_mul_f32_e32 v32, v32, v93
	v_mul_f32_e32 v61, 0.15915494, v32
	v_floor_f32_e32 v61, v61
	v_fma_f32 v32, v32, 0.15915494, -v61
	v_mul_f32_e32 v61, v63, v93
	v_mul_f32_e32 v63, 0.15915494, v61
	v_floor_f32_e32 v63, v63
	v_pk_mul_f32 v[126:127], v[62:63], v[244:245] op_sel_hi:[0,1]
	v_pk_mul_f32 v[34:35], v[34:35], v[126:127]
	v_fma_f32 v61, v61, 0.15915494, -v63
	v_pk_mul_f32 v[118:119], v[34:35], v[118:119] op_sel:[1,0] op_sel_hi:[0,0]
	v_pk_fma_f32 v[126:127], v[34:35], v[116:117], v[118:119] neg_lo:[0,0,1] neg_hi:[0,0,1]
	v_pk_fma_f32 v[34:35], v[34:35], v[116:117], v[118:119] op_sel_hi:[1,0,1]
	v_sin_f32_e32 v220, v32
	v_cvt_pk_bf16_f32 v115, v126, v35
	v_pk_mul_f32 v[34:35], v[62:63], v[242:243] op_sel_hi:[0,1]
	v_pk_mul_f32 v[34:35], v[40:41], v[34:35]
	v_cos_f32_e32 v226, v32
	v_pk_mul_f32 v[40:41], v[34:35], v[122:123] op_sel:[1,0] op_sel_hi:[0,0]
	v_pk_fma_f32 v[116:117], v[34:35], v[120:121], v[40:41] neg_lo:[0,0,1] neg_hi:[0,0,1]
	v_pk_fma_f32 v[34:35], v[34:35], v[120:121], v[40:41] op_sel_hi:[1,0,1]
	v_sin_f32_e32 v218, v61
	v_cvt_pk_bf16_f32 v116, v116, v35
	v_pk_mul_f32 v[34:35], v[62:63], v[240:241] op_sel_hi:[0,1]
	v_pk_mul_f32 v[34:35], v[42:43], v[34:35]
	v_cos_f32_e32 v32, v61
	v_pk_mul_f32 v[40:41], v[34:35], v[128:129] op_sel:[1,0] op_sel_hi:[0,0]
	v_pk_fma_f32 v[42:43], v[34:35], v[124:125], v[40:41] neg_lo:[0,0,1] neg_hi:[0,0,1]
	v_pk_fma_f32 v[34:35], v[34:35], v[124:125], v[40:41] op_sel_hi:[1,0,1]
	s_nop 0
	v_cvt_pk_bf16_f32 v117, v42, v35
	v_pk_mul_f32 v[34:35], v[62:63], v[238:239] op_sel_hi:[0,1]
	v_pk_mul_f32 v[34:35], v[34:35], v[36:37]
	s_nop 0
	v_pk_mul_f32 v[36:37], v[34:35], v[162:163] op_sel:[1,0] op_sel_hi:[0,0]
	v_pk_fma_f32 v[40:41], v[34:35], v[158:159], v[36:37] neg_lo:[0,0,1] neg_hi:[0,0,1]
	v_pk_fma_f32 v[34:35], v[34:35], v[158:159], v[36:37] op_sel_hi:[1,0,1]
	s_nop 0
	v_cvt_pk_bf16_f32 v118, v40, v35
	v_pk_mul_f32 v[34:35], v[62:63], v[64:65] op_sel_hi:[0,1]
	v_pk_mul_f32 v[34:35], v[34:35], v[38:39]
	s_nop 0
	v_pk_mul_f32 v[36:37], v[34:35], v[168:169] op_sel:[1,0] op_sel_hi:[0,0]
	v_pk_fma_f32 v[38:39], v[34:35], v[166:167], v[36:37] neg_lo:[0,0,1] neg_hi:[0,0,1]
	v_pk_fma_f32 v[34:35], v[34:35], v[166:167], v[36:37] op_sel_hi:[1,0,1]
	s_nop 0
	v_cvt_pk_bf16_f32 v119, v38, v35
	v_pk_mul_f32 v[34:35], v[62:63], v[236:237] op_sel_hi:[0,1]
	v_pk_mul_f32 v[34:35], v[34:35], v[52:53]
	s_nop 0
	v_pk_mul_f32 v[36:37], v[34:35], v[172:173] op_sel:[1,0] op_sel_hi:[0,0]
	v_pk_fma_f32 v[38:39], v[34:35], v[170:171], v[36:37] neg_lo:[0,0,1] neg_hi:[0,0,1]
	v_pk_fma_f32 v[34:35], v[34:35], v[170:171], v[36:37] op_sel_hi:[1,0,1]
	s_nop 0
	v_cvt_pk_bf16_f32 v120, v38, v35
	v_pk_mul_f32 v[34:35], v[62:63], v[66:67] op_sel_hi:[0,1]
	v_pk_mul_f32 v[34:35], v[34:35], v[54:55]
	s_nop 0
	v_pk_mul_f32 v[36:37], v[34:35], v[180:181] op_sel:[1,0] op_sel_hi:[0,0]
	v_pk_fma_f32 v[38:39], v[34:35], v[174:175], v[36:37] neg_lo:[0,0,1] neg_hi:[0,0,1]
; __device__ __forceinline__ int v_st(int k, int c) { const int kk = (k & ~0xC) | ((k & 4) << 1) | ((k & 8) >> 1); return ((kk >> 3) * 4 + (c >> 5)) * 512 + ((kk & 7) * 32 + (c & 31)) * 2; }
; __device__ __forceinline__ int v_rd_base(int lane) { return ((lane & 3) << 3) | (((lane >> 2) & 3) << 6) | (((lane >> 4) & 1) << 5) | (((lane >> 5) & 1) << 8); }
; #define QROPE(RW, GA, GB, E2, OUT) do { int pp = (8 * d0 + 4 * hi + (E2)) & 31; asm volatile("" : "+v"(pp)); const float freq = __builtin_amdgcn_exp2f(-(float)pp * (13.287712379549449f / 32.f)); \
;         float sn, cs; sincos_rev(idx * freq * INV2PI, sn, cs); const float y0 = bflo(RW) * rsc * (GA), y1 = bfhi(RW) * rsc * (GB); OUT = cvtpk(y0 * cs - y1 * sn, y0 * sn + y1 * cs); } while (0)
; #define SLOAD(i, k0) do { sr_[i].vs0 = *reinterpret_cast<const bf16x8*>(&Vh[(long)((k0) + sr) * LDK + sc]); sr_[i].vs1 = *reinterpret_cast<const bf16x8*>(&Vh[(long)((k0) + 32 + sr) * LDK + sc]); \
;     sr_[i].ks0 = *reinterpret_cast<const bf16x8*>(&Kh[(long)((k0) + sr) * LDK + sc]); sr_[i].ks1 = *reinterpret_cast<const bf16x8*>(&Kh[(long)((k0) + 32 + sr) * LDK + sc]); } while (0)
; __device__ __forceinline__ void attn_unit_fast(const bf16* __restrict__ Qb, const bf16* __restrict__ Kh, const bf16* __restrict__ Vh, bf16* __restrict__ Ob, int NT, char* lds, int t0, const float* __restrict__ qg) {
;     ...
;     for (int d0 = 0; d0 < 8; ++d0) { const v4u rw = *reinterpret_cast<const v4u*>(Qw + d0 * 16);
;       const f32x4 g0 = *reinterpret_cast<const f32x4*>(qg + 16 * d0 + 8 * hi), g1 = *reinterpret_cast<const f32x4*>(qg + 16 * d0 + 8 * hi + 4);
;       const float idx = d0 < 4 ? frow : fcol; v4u wv;
;     ...
;       QROPE(rw.x, g0.x, g0.y, 0, wv.x); QROPE(rw.y, g0.z, g0.w, 1, wv.y); QROPE(rw.z, g1.x, g1.y, 2, wv.z); QROPE(rw.w, g1.z, g1.w, 3, wv.w);
;     ...
;       qr[d0] = __builtin_bit_cast(bf16x8, wv); }
;   }
;   const int sr = tid >> 4, sc = (tid & 15) * 8, vst0 = v_st(sr, sc), vst1 = v_st(32 + sr, sc);
;   const int vb0 = (int)(uintptr_t)V_lds + v_rd_base(lane);
;   struct { bf16x8 vs0, vs1, ks0, ks1; } sr_[2];
;     ...
;   f32x16 pA0, pA1, pB0, pB1; bf16x8 pa0, pa1, pa2, pa3;
;   constexpr int SE = 0, SO = 1;
;   SLOAD(SE, 0); asm volatile("s_waitcnt vmcnt(0)" ::: "memory"); SWRITE(0, SE); __syncthreads();
	v_pk_fma_f32 v[34:35], v[34:35], v[174:175], v[36:37] op_sel_hi:[1,0,1]
	s_nop 0
	v_cvt_pk_bf16_f32 v121, v38, v35
	v_pk_mul_f32 v[34:35], v[62:63], v[234:235] op_sel_hi:[0,1]
	v_pk_mul_f32 v[34:35], v[34:35], v[44:45]
	s_nop 0
	v_pk_mul_f32 v[36:37], v[34:35], v[186:187] op_sel:[1,0] op_sel_hi:[0,0]
	v_pk_fma_f32 v[38:39], v[34:35], v[184:185], v[36:37] neg_lo:[0,0,1] neg_hi:[0,0,1]
	v_pk_fma_f32 v[34:35], v[34:35], v[184:185], v[36:37] op_sel_hi:[1,0,1]
	s_nop 0
	v_cvt_pk_bf16_f32 v122, v38, v35
	v_pk_mul_f32 v[34:35], v[62:63], v[68:69] op_sel_hi:[0,1]
	v_pk_mul_f32 v[34:35], v[34:35], v[46:47]
	v_ashrrev_i32_e32 v46, 4, v195
	v_pk_mul_f32 v[36:37], v[34:35], v[190:191] op_sel:[1,0] op_sel_hi:[0,0]
	v_pk_fma_f32 v[38:39], v[34:35], v[188:189], v[36:37] neg_lo:[0,0,1] neg_hi:[0,0,1]
	v_pk_fma_f32 v[34:35], v[34:35], v[188:189], v[36:37] op_sel_hi:[1,0,1]
	v_add_u32_e32 v64, 32, v46
	v_cvt_pk_bf16_f32 v123, v38, v35
	v_pk_mul_f32 v[34:35], v[62:63], v[232:233] op_sel_hi:[0,1]
	v_pk_mul_f32 v[4:5], v[34:35], v[4:5]
	v_ashrrev_i32_e32 v47, 31, v46
	v_pk_mul_f32 v[34:35], v[4:5], v[194:195] op_sel:[1,0] op_sel_hi:[0,0]
	v_pk_fma_f32 v[36:37], v[4:5], v[192:193], v[34:35] neg_lo:[0,0,1] neg_hi:[0,0,1]
	v_pk_fma_f32 v[4:5], v[4:5], v[192:193], v[34:35] op_sel_hi:[1,0,1]
	v_lshlrev_b64 v[34:35], 8, v[46:47]
	v_and_b32_e32 v4, 0x78, v33
	v_lshlrev_b32_e32 v61, 1, v4
	v_ashrrev_i32_e32 v65, 31, v64
	v_cvt_pk_bf16_f32 v124, v36, v5
	v_or_b32_e32 v36, v34, v61
	v_mov_b32_e32 v37, v35
	v_lshlrev_b64 v[52:53], 8, v[64:65]
	v_lshl_add_u64 v[4:5], s[66:67], 0, v[36:37]
	v_or_b32_e32 v52, v52, v61
	global_load_dwordx4 v[38:41], v[4:5], off
	v_lshl_add_u64 v[4:5], s[66:67], 0, v[52:53]
	global_load_dwordx4 v[42:45], v[4:5], off
	v_pk_mul_f32 v[4:5], v[62:63], v[70:71] op_sel_hi:[0,1]
	v_pk_mul_f32 v[54:55], v[4:5], v[6:7]
	v_lshl_add_u64 v[4:5], s[44:45], 0, v[36:37]
	global_load_dwordx4 v[4:7], v[4:5], off
	v_pk_mul_f32 v[66:67], v[54:55], v[94:95] op_sel:[1,0] op_sel_hi:[0,0]
	v_lshl_add_u64 v[52:53], s[44:45], 0, v[52:53]
	v_pk_fma_f32 v[68:69], v[54:55], v[92:93], v[66:67] neg_lo:[0,0,1] neg_hi:[0,0,1]
	v_pk_fma_f32 v[66:67], v[54:55], v[92:93], v[66:67] op_sel_hi:[1,0,1]
	global_load_dwordx4 v[52:55], v[52:53], off
	v_cvt_pk_bf16_f32 v125, v68, v67
	v_pk_mul_f32 v[66:67], v[62:63], v[202:203] op_sel_hi:[0,1]
	v_pk_mul_f32 v[0:1], v[66:67], v[0:1]
	s_waitcnt vmcnt(0)
	s_nop 0
	v_pk_mul_f32 v[66:67], v[0:1], v[98:99] op_sel:[1,0] op_sel_hi:[0,0]
	v_pk_fma_f32 v[68:69], v[0:1], v[96:97], v[66:67] neg_lo:[0,0,1] neg_hi:[0,0,1]
	v_pk_fma_f32 v[0:1], v[0:1], v[96:97], v[66:67] op_sel_hi:[1,0,1]
	s_nop 0
	v_cvt_pk_bf16_f32 v126, v68, v1
	v_pk_mul_f32 v[0:1], v[62:63], v[72:73] op_sel_hi:[0,1]
	v_pk_mul_f32 v[0:1], v[0:1], v[2:3]
	s_nop 0
	v_pk_mul_f32 v[2:3], v[0:1], v[102:103] op_sel:[1,0] op_sel_hi:[0,0]
	v_pk_fma_f32 v[66:67], v[0:1], v[104:105], v[2:3] neg_lo:[0,0,1] neg_hi:[0,0,1]
	v_pk_fma_f32 v[0:1], v[0:1], v[104:105], v[2:3] op_sel_hi:[1,0,1]
	s_nop 0
	v_cvt_pk_bf16_f32 v127, v66, v1
	v_pk_mul_f32 v[0:1], v[62:63], v[200:201] op_sel_hi:[0,1]
	s_waitcnt vmcnt(10)
	v_pk_mul_f32 v[0:1], v[0:1], v[12:13]
	s_nop 0
	v_pk_mul_f32 v[2:3], v[0:1], v[108:109] op_sel:[1,0] op_sel_hi:[0,0]
	v_pk_fma_f32 v[12:13], v[0:1], v[106:107], v[2:3] neg_lo:[0,0,1] neg_hi:[0,0,1]
	v_pk_fma_f32 v[0:1], v[0:1], v[106:107], v[2:3] op_sel_hi:[1,0,1]
	s_nop 0
	v_cvt_pk_bf16_f32 v128, v12, v1
	v_pk_mul_f32 v[0:1], v[62:63], v[74:75] op_sel_hi:[0,1]
	v_pk_mul_f32 v[0:1], v[0:1], v[14:15]
	s_nop 0
	v_pk_mul_f32 v[2:3], v[0:1], v[130:131] op_sel:[1,0] op_sel_hi:[0,0]
	v_pk_fma_f32 v[12:13], v[0:1], v[132:133], v[2:3] neg_lo:[0,0,1] neg_hi:[0,0,1]
	v_pk_fma_f32 v[0:1], v[0:1], v[132:133], v[2:3] op_sel_hi:[1,0,1]
	s_nop 0
	v_cvt_pk_bf16_f32 v129, v12, v1
	v_pk_mul_f32 v[0:1], v[62:63], v[198:199] op_sel_hi:[0,1]
	v_pk_mul_f32 v[0:1], v[0:1], v[8:9]
	s_nop 0
	v_pk_mul_f32 v[2:3], v[0:1], v[142:143] op_sel:[1,0] op_sel_hi:[0,0]
	v_pk_fma_f32 v[8:9], v[0:1], v[138:139], v[2:3] neg_lo:[0,0,1] neg_hi:[0,0,1]
	v_pk_fma_f32 v[0:1], v[0:1], v[138:139], v[2:3] op_sel_hi:[1,0,1]
	s_nop 0
	v_cvt_pk_bf16_f32 v130, v8, v1
	v_pk_mul_f32 v[0:1], v[62:63], v[76:77] op_sel_hi:[0,1]
	v_pk_mul_f32 v[0:1], v[0:1], v[10:11]
	v_and_b32_e32 v10, 0xfffff0, v64
	v_pk_mul_f32 v[2:3], v[0:1], v[144:145] op_sel:[1,0] op_sel_hi:[0,0]
	v_pk_fma_f32 v[8:9], v[0:1], v[146:147], v[2:3] neg_lo:[0,0,1] neg_hi:[0,0,1]
	v_pk_fma_f32 v[0:1], v[0:1], v[146:147], v[2:3] op_sel_hi:[1,0,1]
	v_lshlrev_b32_e32 v11, 1, v64
	v_cvt_pk_bf16_f32 v131, v8, v1
	v_pk_mul_f32 v[0:1], v[62:63], v[196:197] op_sel_hi:[0,1]
	s_waitcnt vmcnt(8)
	v_pk_mul_f32 v[0:1], v[0:1], v[28:29]
	v_and_or_b32 v10, v11, 8, v10
	v_pk_mul_f32 v[2:3], v[0:1], v[150:151] op_sel:[1,0] op_sel_hi:[0,0]
	v_pk_fma_f32 v[8:9], v[0:1], v[148:149], v[2:3] neg_lo:[0,0,1] neg_hi:[0,0,1]
	v_pk_fma_f32 v[0:1], v[0:1], v[148:149], v[2:3] op_sel_hi:[1,0,1]
	v_bfe_u32 v2, v33, 5, 2
	v_cvt_pk_bf16_f32 v132, v8, v1
	v_pk_mul_f32 v[0:1], v[62:63], v[78:79] op_sel_hi:[0,1]
	v_pk_mul_f32 v[8:9], v[0:1], v[30:31]
	v_and_b32_e32 v0, 0xfffff0, v46
	v_lshlrev_b32_e32 v1, 1, v46
	v_and_or_b32 v0, v1, 8, v0
	v_lshrrev_b32_e32 v1, 1, v46
	v_lshrrev_b32_e32 v0, 1, v0
	v_and_b32_e32 v3, 3, v46
	v_lshrrev_b32_e32 v10, 1, v10
	v_or_b32_e32 v0, v0, v2
	v_and_or_b32 v1, v1, 4, v3
	v_or_b32_e32 v2, v10, v2
	v_lshlrev_b32_e32 v0, 9, v0
	v_lshlrev_b32_e32 v1, 6, v1
	v_and_b32_e32 v3, 48, v61
	v_lshlrev_b32_e32 v2, 9, v2
	v_or3_b32 v0, v0, v1, v3
	v_or3_b32 v1, v2, v1, v3
	v_add_u32_e32 v184, 0, v0
	v_add_u32_e32 v186, 0, v1
	v_lshlrev_b32_e32 v0, 8, v46
	v_and_b32_e32 v1, 0x70, v195
	v_bitop3_b32 v0, v61, v0, v1 bitop3:0xde
	v_lshlrev_b32_e32 v33, 4, v195
	v_add_u32_e32 v190, 0x10800, v0
	v_lshlrev_b32_e32 v0, 8, v64
	s_waitcnt vmcnt(3)
	ds_write_b128 v184, v[38:41]
	s_waitcnt vmcnt(2)
	ds_write_b128 v186, v[42:45]
	v_bitop3_b32 v0, v61, v0, v1 bitop3:0xde
	v_lshlrev_b32_e32 v42, 8, v191
	v_and_b32_e32 v43, 0x70, v33
	s_waitcnt vmcnt(1)
	ds_write_b128 v190, v[4:7]
	v_add_u32_e32 v192, 0x10800, v0
	v_bitop3_b32 v0, v176, v42, v43 bitop3:0xde
	v_pk_mul_f32 v[4:5], v[8:9], v[110:111] op_sel:[1,0] op_sel_hi:[0,0]
	v_add_u32_e32 v194, 0x10800, v0
	v_pk_fma_f32 v[6:7], v[8:9], v[134:135], v[4:5] neg_lo:[0,0,1] neg_hi:[0,0,1]
	v_pk_fma_f32 v[4:5], v[8:9], v[134:135], v[4:5] op_sel_hi:[1,0,1]
	s_waitcnt vmcnt(0)
	ds_write_b128 v192, v[52:55]
	s_waitcnt lgkmcnt(0)
	s_barrier
; __device__ __forceinline__ int v_st(int k, int c) { const int kk = (k & ~0xC) | ((k & 4) << 1) | ((k & 8) >> 1); return ((kk >> 3) * 4 + (c >> 5)) * 512 + ((kk & 7) * 32 + (c & 31)) * 2; }
; __device__ __forceinline__ int v_rd_base(int lane) { return ((lane & 3) << 3) | (((lane >> 2) & 3) << 6) | (((lane >> 4) & 1) << 5) | (((lane >> 5) & 1) << 8); }
; #define QROPE(RW, GA, GB, E2, OUT) do { int pp = (8 * d0 + 4 * hi + (E2)) & 31; asm volatile("" : "+v"(pp)); const float freq = __builtin_amdgcn_exp2f(-(float)pp * (13.287712379549449f / 32.f)); \
;         float sn, cs; sincos_rev(idx * freq * INV2PI, sn, cs); const float y0 = bflo(RW) * rsc * (GA), y1 = bfhi(RW) * rsc * (GB); OUT = cvtpk(y0 * cs - y1 * sn, y0 * sn + y1 * cs); } while (0)
; #define SWAIT() asm volatile("s_waitcnt vmcnt(4)" ::: "memory")
; __device__ __forceinline__ void attn_unit_fast(const bf16* __restrict__ Qb, const bf16* __restrict__ Kh, const bf16* __restrict__ Vh, bf16* __restrict__ Ob, int NT, char* lds, int t0, const float* __restrict__ qg) {
;     ...
;     for (int d0 = 0; d0 < 8; ++d0) { const v4u rw = *reinterpret_cast<const v4u*>(Qw + d0 * 16);
;       const f32x4 g0 = *reinterpret_cast<const f32x4*>(qg + 16 * d0 + 8 * hi), g1 = *reinterpret_cast<const f32x4*>(qg + 16 * d0 + 8 * hi + 4);
;       const float idx = d0 < 4 ? frow : fcol; v4u wv;
;     ...
;       QROPE(rw.x, g0.x, g0.y, 0, wv.x); QROPE(rw.y, g0.z, g0.w, 1, wv.y); QROPE(rw.z, g1.x, g1.y, 2, wv.z); QROPE(rw.w, g1.z, g1.w, 3, wv.w);
;     ...
;       qr[d0] = __builtin_bit_cast(bf16x8, wv); }
;     ...
;   const int sr = tid >> 4, sc = (tid & 15) * 8, vst0 = v_st(sr, sc), vst1 = v_st(32 + sr, sc);
;   const int vb0 = (int)(uintptr_t)V_lds + v_rd_base(lane);
;   struct { bf16x8 vs0, vs1, ks0, ks1; } sr_[2];
;     ...
;   f32x16 pA0, pA1, pB0, pB1; bf16x8 pa0, pa1, pa2, pa3;
;   constexpr int SE = 0, SO = 1;
;   SLOAD(SE, 0); asm volatile("s_waitcnt vmcnt(0)" ::: "memory"); SWRITE(0, SE); __syncthreads();
;   qkt(pA0, pA1, K_lds, qr, r32, hi); partialSM_fast(pA0, pA1);
;   SLOAD(SO, KVBLK); SLOAD(SE, 2 * KVBLK);
;   SWAIT(); SWRITE(1, SO); __syncthreads();
	s_add_u32 s0, s48, s0
	s_addc_u32 s1, s49, s1
	v_readfirstlane_b32 s5, v195
	v_lshrrev_b32_e32 v245, 4, v195
	v_xor_b32_e32 v244, v245, v195
	v_and_b32_e32 v244, 15, v244
	v_lshlrev_b32_e32 v244, 4, v244
	v_lshl_or_b32 v244, v245, 8, v244
	v_add_u32_e32 v244, 0x6404000, v244
	v_add_u32_e32 v245, 0x2000, v244
	v_bfe_u32 v254, v195, 2, 3
	v_bfe_u32 v253, v195, 7, 2
	v_lshl_or_b32 v254, v253, 3, v254
	v_bfe_u32 v253, v195, 5, 2
	v_lshlrev_b32_e32 v253, 6, v253
	v_lshl_or_b32 v253, v254, 8, v253
	v_and_b32_e32 v254, 3, v195
	v_lshl_or_b32 v253, v254, 4, v253
	v_add_u32_e32 v253, 0x7100000, v253
	v_add_u32_e32 v254, 0x2000, v253
	s_lshl_b32 s5, s5, 4
	s_add_u32 m0, s5, 0x0
	s_nop 0
	global_load_lds_dwordx4 v253, s[0:1]
	s_add_u32 m0, s5, 0x2000
	s_nop 0
	global_load_lds_dwordx4 v254, s[0:1]
	s_add_u32 m0, s5, 0x14800
	s_nop 0
	global_load_lds_dwordx4 v244, s[0:1]
	s_add_u32 m0, s5, 0x16800
	s_nop 0
	global_load_lds_dwordx4 v245, s[0:1]
	s_add_u32 s0, s0, 0x4000
	s_addc_u32 s1, s1, 0
	s_add_u32 m0, s5, 0x18800
	s_nop 0
	global_load_lds_dwordx4 v244, s[0:1]
	s_add_u32 m0, s5, 0x1a800
	s_nop 0
	global_load_lds_dwordx4 v245, s[0:1]
	s_add_u32 m0, s5, 0x4000
	s_nop 0
	global_load_lds_dwordx4 v253, s[0:1]
	s_add_u32 m0, s5, 0x6000
	s_nop 0
	global_load_lds_dwordx4 v254, s[0:1]
	s_add_u32 s0, s0, 0x4000
	s_addc_u32 s1, s1, 0
	s_add_u32 m0, s5, 0x1c800
	s_nop 0
	global_load_lds_dwordx4 v244, s[0:1]
	s_add_u32 m0, s5, 0x1e800
	s_nop 0
	global_load_lds_dwordx4 v245, s[0:1]
	s_add_u32 m0, s5, 0x8000
	s_nop 0
	global_load_lds_dwordx4 v253, s[0:1]
	s_add_u32 m0, s5, 0xa000
	s_nop 0
	global_load_lds_dwordx4 v254, s[0:1]
	s_add_u32 s0, s0, 0x4000
	s_addc_u32 s1, s1, 0
	ds_read_b128 v[0:3], v194
	ds_read_b128 v[28:31], v194 offset:8192
	v_cvt_pk_bf16_f32 v133, v6, v5
	v_pk_mul_f32 v[4:5], v[62:63], v[182:183] op_sel_hi:[0,1]
	v_pk_mul_f32 v[20:21], v[4:5], v[20:21]
	s_waitcnt lgkmcnt(0)
	v_mfma_f32_32x32x16_bf16 v[64:79], v[28:31], v[112:115], 0
	v_mul_f32_e64 v38, v21, v140
	v_mul_f32_e64 v39, v20, v140
	v_fma_f32 v40, v20, v136, -v38
	v_fma_f32 v41, v21, v137, -v39
	v_fma_f32 v20, v20, v136, v38
	v_fma_f32 v21, v21, v136, v39
	v_mov_b32_e32 v197, 0
	v_or_b32_e32 v20, 32, v176
	v_bitop3_b32 v20, v20, v42, v43 bitop3:0xde
	v_cvt_pk_bf16_f32 v134, v40, v21
	v_add_u32_e32 v196, 0x10800, v20
	v_pk_mul_f32 v[20:21], v[62:63], v[80:81] op_sel_hi:[0,1]
	v_pk_mul_f32 v[20:21], v[20:21], v[22:23]
	ds_read_b128 v[38:41], v196
	v_pk_mul_f32 v[22:23], v[20:21], v[60:61] op_sel:[1,0] op_sel_hi:[0,0]
	v_pk_fma_f32 v[28:29], v[20:21], v[204:205], v[22:23] neg_lo:[0,0,1] neg_hi:[0,0,1]
	v_pk_fma_f32 v[20:21], v[20:21], v[204:205], v[22:23] op_sel_hi:[1,0,1]
	v_mfma_f32_32x32x16_bf16 v[0:15], v[0:3], v[112:115], 0
	v_cvt_pk_bf16_f32 v135, v28, v21
	ds_read_b128 v[20:23], v196 offset:8192
	v_mul_f32_e64 v28, v62, v154
	v_mul_f32_e64 v29, v62, v155
	v_mul_f32_e64 v24, v28, v24
	v_mul_f32_e64 v25, v29, v25
	v_or_b32_e32 v28, 64, v176
	v_bitop3_b32 v28, v28, v42, v43 bitop3:0xde
	v_add_u32_e32 v198, 0x10800, v28
	ds_read_b128 v[28:31], v198
	s_waitcnt lgkmcnt(2)
	v_mfma_f32_32x32x16_bf16 v[0:15], v[38:41], v[116:119], v[0:15]
	v_mul_f32_e64 v38, v25, v208
	v_mul_f32_e64 v39, v24, v208
	v_mov_b32_e32 v40, v197
	v_mov_b32_e32 v41, v197
	v_mov_b32_e32 v44, v197
	v_mov_b32_e32 v45, v197
	v_mov_b32_e32 v46, v197
	v_mov_b32_e32 v47, v197
	s_waitcnt lgkmcnt(1)
	v_mfma_f32_32x32x16_bf16 v[64:79], v[20:23], v[116:119], v[64:79]
	v_fma_f32 v20, v24, v206, -v38
	v_fma_f32 v21, v25, v207, -v39
	v_fma_f32 v22, v24, v206, v38
	v_fma_f32 v23, v25, v206, v39
	v_mov_b32_e32 v52, v197
	v_cvt_pk_bf16_f32 v136, v20, v23
	v_pk_mul_f32 v[20:21], v[62:63], v[82:83] op_sel_hi:[0,1]
	v_pk_mul_f32 v[24:25], v[20:21], v[26:27]
	ds_read_b128 v[20:23], v198 offset:8192
	v_pk_mul_f32 v[26:27], v[24:25], v[210:211] op_sel:[1,0] op_sel_hi:[0,0]
	s_waitcnt lgkmcnt(1)
	v_mfma_f32_32x32x16_bf16 v[0:15], v[28:31], v[120:123], v[0:15]
	v_fma_f32 v28, v24, v216, -v26
	v_fma_f32 v29, v25, v217, -v27
	v_fma_f32 v24, v24, v216, v26
	v_fma_f32 v25, v25, v216, v27
	v_lshl_add_u64 v[30:31], v[36:37], 0, s[30:31]
	v_or_b32_e32 v24, 0x60, v176
	v_bitop3_b32 v24, v24, v42, v43 bitop3:0xde
	v_add_u32_e32 v199, 0x10800, v24
	v_cvt_pk_bf16_f32 v137, v28, v25
	ds_read_b128 v[24:27], v199
	s_waitcnt lgkmcnt(1)
	v_mfma_f32_32x32x16_bf16 v[64:79], v[20:23], v[120:123], v[64:79]
	v_mul_f32_e64 v20, v62, v152
	v_mul_f32_e64 v21, v62, v153
	v_mul_f32_e64 v16, v20, v16
	v_mul_f32_e64 v17, v21, v17
	v_lshl_add_u64 v[38:39], s[66:67], 0, v[30:31]
	v_pk_mul_f32 v[20:21], v[16:17], v[230:231] op_sel:[1,0] op_sel_hi:[0,0]
	v_pk_fma_f32 v[22:23], v[16:17], v[228:229], v[20:21] neg_lo:[0,0,1] neg_hi:[0,0,1]
	v_pk_fma_f32 v[16:17], v[16:17], v[228:229], v[20:21] op_sel_hi:[1,0,1]
	v_mov_b32_e32 v53, v197
	v_cvt_pk_bf16_f32 v138, v22, v17
	ds_read_b128 v[20:23], v199 offset:8192
	v_or_b32_e32 v16, 0x80, v176
	v_bitop3_b32 v16, v16, v42, v43 bitop3:0xde
	v_add_u32_e32 v200, 0x10800, v16
	v_lshl_add_u64 v[16:17], v[36:37], 0, s[24:25]
	s_waitcnt lgkmcnt(1)
	v_mfma_f32_32x32x16_bf16 v[0:15], v[24:27], v[124:127], v[0:15]
	ds_read_b128 v[24:27], v200
	v_lshl_add_u64 v[28:29], s[66:67], 0, v[16:17]
	v_lshl_add_u64 v[16:17], s[44:45], 0, v[16:17]
	v_lshl_add_u64 v[28:29], s[44:45], 0, v[30:31]
	v_pk_mul_f32 v[16:17], v[62:63], v[84:85] op_sel_hi:[0,1]
	v_pk_mul_f32 v[16:17], v[16:17], v[18:19]
	s_waitcnt lgkmcnt(1)
	v_mfma_f32_32x32x16_bf16 v[64:79], v[20:23], v[124:127], v[64:79]
	v_mul_f32_e64 v18, v17, v212
	v_mul_f32_e64 v19, v16, v212
	v_fma_f32 v20, v16, v164, -v18
	v_fma_f32 v21, v17, v165, -v19
	v_fma_f32 v16, v16, v164, v18
	v_fma_f32 v17, v17, v164, v19
	v_mov_b32_e32 v28, v197
	v_cvt_pk_bf16_f32 v139, v20, v17
	ds_read_b128 v[16:19], v200 offset:8192
	v_pk_mul_f32 v[20:21], v[62:63], v[100:101] op_sel_hi:[0,1]
	s_waitcnt lgkmcnt(1)
; #define QROPE(RW, GA, GB, E2, OUT) do { int pp = (8 * d0 + 4 * hi + (E2)) & 31; asm volatile("" : "+v"(pp)); const float freq = __builtin_amdgcn_exp2f(-(float)pp * (13.287712379549449f / 32.f)); \
;         float sn, cs; sincos_rev(idx * freq * INV2PI, sn, cs); const float y0 = bflo(RW) * rsc * (GA), y1 = bfhi(RW) * rsc * (GB); OUT = cvtpk(y0 * cs - y1 * sn, y0 * sn + y1 * cs); } while (0)
; __device__ __forceinline__ void partialSM_fast(f32x16& p0, f32x16& p1) {
; #pragma unroll
;   for (int r = 0; r < 16; ++r) p0[r] = __builtin_amdgcn_exp2f(p0[r]);
; }
; __device__ __forceinline__ void finishSM_fast(f32x16& p0, f32x16& p1, float& l_reg, bf16x8& pa0, bf16x8& pa1, bf16x8& pa2, bf16x8& pa3) {
; #pragma unroll
;   for (int r = 0; r < 16; ++r) p1[r] = __builtin_amdgcn_exp2f(p1[r]);
;   float ps = 0;
; #pragma unroll
;   for (int r = 0; r < 16; ++r) ps += p0[r];
; #pragma unroll
;   for (int r = 0; r < 16; ++r) ps += p1[r];
;   { auto rr = __builtin_amdgcn_permlane32_swap(__float_as_uint(ps), __float_as_uint(ps), false, false);
;     ps = __uint_as_float(rr[0]) + __uint_as_float(rr[1]); }
;   l_reg += ps;
;     ...
;   PK4(p0, 0, pa0); PK4(p0, 8, pa1); PK4(p1, 0, pa2); PK4(p1, 8, pa3);
;     ...
; }
; __device__ __forceinline__ void attn_unit_fast(const bf16* __restrict__ Qb, const bf16* __restrict__ Kh, const bf16* __restrict__ Vh, bf16* __restrict__ Ob, int NT, char* lds, int t0, const float* __restrict__ qg) {
;     ...
;     for (int d0 = 0; d0 < 8; ++d0) { const v4u rw = *reinterpret_cast<const v4u*>(Qw + d0 * 16);
;       const f32x4 g0 = *reinterpret_cast<const f32x4*>(qg + 16 * d0 + 8 * hi), g1 = *reinterpret_cast<const f32x4*>(qg + 16 * d0 + 8 * hi + 4);
;       const float idx = d0 < 4 ? frow : fcol; v4u wv;
;     ...
;       QROPE(rw.x, g0.x, g0.y, 0, wv.x); QROPE(rw.y, g0.z, g0.w, 1, wv.y); QROPE(rw.z, g1.x, g1.y, 2, wv.z); QROPE(rw.w, g1.z, g1.w, 3, wv.w);
;     ...
;       qr[d0] = __builtin_bit_cast(bf16x8, wv); }
	v_mfma_f32_32x32x16_bf16 v[0:15], v[24:27], v[128:131], v[0:15]
	v_mul_f32_e64 v24, v20, v56
	v_mul_f32_e64 v25, v21, v57
	v_or_b32_e32 v20, 0xa0, v176
	v_bitop3_b32 v20, v20, v42, v43 bitop3:0xde
	v_add_u32_e32 v201, 0x10800, v20
	ds_read_b128 v[20:23], v201
	v_pk_mul_f32 v[26:27], v[24:25], v[214:215] op_sel:[1,0] op_sel_hi:[0,0]
	v_mov_b32_e32 v29, v197
	s_waitcnt lgkmcnt(1)
	v_mfma_f32_32x32x16_bf16 v[64:79], v[16:19], v[128:131], v[64:79]
	v_fma_f32 v16, v24, v160, -v26
	v_fma_f32 v17, v25, v161, -v27
	v_fma_f32 v18, v24, v160, v26
	v_fma_f32 v19, v25, v160, v27
	v_mov_b32_e32 v30, v197
	v_cvt_pk_bf16_f32 v148, v16, v19
	v_pk_mul_f32 v[16:17], v[62:63], v[86:87] op_sel_hi:[0,1]
	v_pk_mul_f32 v[24:25], v[16:17], v[58:59]
	ds_read_b128 v[16:19], v201 offset:8192
	v_pk_mul_f32 v[26:27], v[24:25], v[222:223] op_sel:[1,0] op_sel_hi:[0,0]
	s_waitcnt lgkmcnt(1)
	v_mfma_f32_32x32x16_bf16 v[0:15], v[20:23], v[132:135], v[0:15]
	v_fma_f32 v20, v24, v224, -v26
	v_fma_f32 v21, v25, v225, -v27
	v_fma_f32 v22, v24, v224, v26
	v_fma_f32 v23, v25, v224, v27
	v_mov_b32_e32 v31, v197
	v_cvt_pk_bf16_f32 v149, v20, v23
	v_or_b32_e32 v20, 0xc0, v176
	v_bitop3_b32 v20, v20, v42, v43 bitop3:0xde
	v_add_u32_e32 v202, 0x10800, v20
	ds_read_b128 v[20:23], v202
	s_waitcnt lgkmcnt(1)
	v_mfma_f32_32x32x16_bf16 v[64:79], v[16:19], v[132:135], v[64:79]
	v_mul_f32_e64 v16, v62, v90
	v_mul_f32_e64 v17, v62, v91
	v_mul_f32_e64 v16, v16, v48
	v_mul_f32_e64 v17, v17, v49
	v_mov_b32_e32 v38, v197
	v_pk_mul_f32 v[18:19], v[16:17], v[220:221] op_sel:[1,0] op_sel_hi:[0,0]
	v_pk_fma_f32 v[24:25], v[16:17], v[226:227], v[18:19] neg_lo:[0,0,1] neg_hi:[0,0,1]
	v_pk_fma_f32 v[16:17], v[16:17], v[226:227], v[18:19] op_sel_hi:[1,0,1]
	v_mov_b32_e32 v39, v197
	v_cvt_pk_bf16_f32 v150, v24, v17
	ds_read_b128 v[16:19], v202 offset:8192
	s_waitcnt lgkmcnt(1)
	v_mfma_f32_32x32x16_bf16 v[0:15], v[20:23], v[136:139], v[0:15]
	v_mul_f32_e64 v20, v62, v88
	v_mul_f32_e64 v21, v62, v89
	v_mul_f32_e64 v24, v20, v50
	v_mul_f32_e64 v25, v21, v51
	v_or_b32_e32 v20, 0xe0, v176
	v_bitop3_b32 v20, v20, v42, v43 bitop3:0xde
	v_pk_mul_f32 v[26:27], v[24:25], v[218:219] op_sel:[1,0] op_sel_hi:[0,0]
	v_add_u32_e32 v203, 0x10800, v20
	ds_read_b128 v[20:23], v203
	s_waitcnt lgkmcnt(1)
	v_mfma_f32_32x32x16_bf16 v[64:79], v[16:19], v[136:139], v[64:79]
	v_fma_f32 v16, v24, v32, -v26
	v_fma_f32 v17, v25, v33, -v27
	v_fma_f32 v18, v24, v32, v26
	v_fma_f32 v19, v25, v32, v27
	v_lshlrev_b32_e32 v24, 3, v179
	v_cvt_pk_bf16_f32 v151, v16, v19
	v_and_b32_e32 v16, 0xc0, v33
	v_and_or_b32 v25, v24, 24, v16
	ds_read_b128 v[16:19], v203 offset:8192
	s_waitcnt lgkmcnt(1)
	v_mfma_f32_32x32x16_bf16 v[0:15], v[20:23], v[148:151], v[0:15]
	v_lshlrev_b32_e32 v20, 1, v195
	v_and_b32_e32 v20, 32, v20
	v_and_b32_e32 v21, 0x100, v24
	v_or3_b32 v24, v25, v20, v21
	v_lshl_add_u64 v[20:21], v[36:37], 0, s[38:39]
	v_lshl_add_u64 v[22:23], s[66:67], 0, v[20:21]
	v_add_u32_e32 v188, s4, v24
	s_waitcnt lgkmcnt(0)
	v_mfma_f32_32x32x16_bf16 v[64:79], v[16:19], v[148:151], v[64:79]
	v_lshl_add_u64 v[16:17], v[36:37], 0, s[34:35]
	v_lshl_add_u64 v[18:19], s[66:67], 0, v[16:17]
	v_lshl_add_u64 v[16:17], s[44:45], 0, v[16:17]
	v_lshl_add_u64 v[18:19], s[44:45], 0, v[20:21]
	s_nop 7
	s_nop 7
	v_and_b32_e32 v204, 15, v191
	v_xor_b32_e32 v204, v204, v193
	v_lshlrev_b32_e32 v204, 4, v204
	v_lshlrev_b32_e32 v205, 8, v191
	v_add_u32_e32 v205, 0x10800, v205
	v_xor_b32_e32 v194, 0x0, v204
	v_add_u32_e32 v194, v194, v205
	v_xor_b32_e32 v196, 0x20, v204
	v_add_u32_e32 v196, v196, v205
	v_xor_b32_e32 v198, 0x40, v204
	v_add_u32_e32 v198, v198, v205
	v_xor_b32_e32 v199, 0x60, v204
	v_add_u32_e32 v199, v199, v205
	v_xor_b32_e32 v200, 0x80, v204
	v_add_u32_e32 v200, v200, v205
	v_xor_b32_e32 v201, 0xa0, v204
	v_add_u32_e32 v201, v201, v205
	v_xor_b32_e32 v202, 0xc0, v204
	v_add_u32_e32 v202, v202, v205
	v_xor_b32_e32 v203, 0xe0, v204
	v_add_u32_e32 v203, v203, v205
	v_exp_f32_e32 v96, v0
	v_exp_f32_e32 v97, v1
	v_exp_f32_e32 v98, v2
	v_exp_f32_e32 v99, v3
	v_exp_f32_e32 v100, v4
	v_exp_f32_e32 v101, v5
	v_exp_f32_e32 v102, v6
	v_exp_f32_e32 v103, v7
	v_exp_f32_e32 v104, v8
	v_exp_f32_e32 v105, v9
	v_exp_f32_e32 v106, v10
	v_exp_f32_e32 v107, v11
	v_exp_f32_e32 v108, v12
	v_exp_f32_e32 v109, v13
	v_exp_f32_e32 v110, v14
	v_exp_f32_e32 v111, v15
	v_exp_f32_e32 v64, v64
	v_exp_f32_e32 v65, v65
	v_exp_f32_e32 v66, v66
	v_exp_f32_e32 v67, v67
	v_exp_f32_e32 v68, v68
	v_exp_f32_e32 v69, v69
	v_exp_f32_e32 v70, v70
	v_exp_f32_e32 v71, v71
	v_exp_f32_e32 v72, v72
	v_exp_f32_e32 v73, v73
	v_exp_f32_e32 v74, v74
	v_exp_f32_e32 v75, v75
	v_exp_f32_e32 v76, v76
	v_exp_f32_e32 v77, v77
	v_exp_f32_e32 v78, v78
	v_exp_f32_e32 v79, v79
	v_cvt_pk_bf16_f32 v140, v96, v97
	v_cvt_pk_bf16_f32 v141, v98, v99
	v_cvt_pk_bf16_f32 v142, v100, v101
	v_cvt_pk_bf16_f32 v143, v102, v103
	v_cvt_pk_bf16_f32 v144, v104, v105
	v_cvt_pk_bf16_f32 v145, v106, v107
	v_cvt_pk_bf16_f32 v146, v108, v109
	v_cvt_pk_bf16_f32 v147, v110, v111
	v_mov_b32_e32 v197, 0
	v_add_f32_e32 v238, v96, v97
	v_add_f32_e32 v238, v98, v238
	v_add_f32_e32 v238, v99, v238
	v_add_f32_e32 v238, v100, v238
	v_add_f32_e32 v238, v101, v238
	v_add_f32_e32 v238, v102, v238
	v_add_f32_e32 v238, v103, v238
	v_add_f32_e32 v238, v104, v238
	v_add_f32_e32 v238, v105, v238
	v_add_f32_e32 v238, v106, v238
	v_add_f32_e32 v238, v107, v238
	v_add_f32_e32 v238, v108, v238
	v_add_f32_e32 v238, v109, v238
	v_add_f32_e32 v238, v110, v238
	v_add_f32_e32 v238, v111, v238
	v_add_f32_e32 v197, v238, v197
	v_mov_b32_e32 v0, 0
	v_mov_b32_e32 v1, 0
	v_mov_b32_e32 v2, 0
	v_mov_b32_e32 v3, 0
	v_mov_b32_e32 v4, 0
	v_mov_b32_e32 v5, 0
	v_mov_b32_e32 v6, 0
	v_mov_b32_e32 v7, 0
	v_mov_b32_e32 v8, 0
	v_mov_b32_e32 v9, 0
	v_mov_b32_e32 v10, 0
	v_mov_b32_e32 v11, 0
	v_mov_b32_e32 v12, 0
	v_mov_b32_e32 v13, 0
	v_mov_b32_e32 v14, 0
	v_mov_b32_e32 v15, 0
	v_mov_b32_e32 v16, 0
	v_mov_b32_e32 v17, 0
	v_mov_b32_e32 v18, 0
	v_mov_b32_e32 v19, 0
	v_mov_b32_e32 v20, 0
	v_mov_b32_e32 v21, 0
	v_mov_b32_e32 v22, 0
	v_mov_b32_e32 v23, 0
	v_mov_b32_e32 v24, 0
	v_mov_b32_e32 v25, 0
	v_mov_b32_e32 v26, 0
	v_mov_b32_e32 v27, 0
	v_mov_b32_e32 v28, 0
	v_mov_b32_e32 v29, 0
	v_mov_b32_e32 v30, 0
	v_mov_b32_e32 v31, 0
	v_mov_b32_e32 v32, 0
	v_mov_b32_e32 v33, 0
	v_mov_b32_e32 v34, 0
	v_mov_b32_e32 v35, 0
	v_mov_b32_e32 v36, 0
	v_mov_b32_e32 v37, 0
	v_mov_b32_e32 v38, 0
	v_mov_b32_e32 v39, 0
	v_mov_b32_e32 v40, 0
	v_mov_b32_e32 v41, 0
	v_mov_b32_e32 v42, 0
	v_mov_b32_e32 v43, 0
	v_mov_b32_e32 v44, 0
	v_mov_b32_e32 v45, 0
	v_mov_b32_e32 v46, 0
	v_mov_b32_e32 v47, 0
	v_mov_b32_e32 v48, 0
	v_mov_b32_e32 v49, 0
	v_mov_b32_e32 v50, 0
	v_mov_b32_e32 v51, 0
	v_mov_b32_e32 v52, 0
	v_mov_b32_e32 v53, 0
	v_mov_b32_e32 v54, 0
	v_mov_b32_e32 v55, 0
	v_mov_b32_e32 v56, 0
	v_mov_b32_e32 v57, 0
	v_mov_b32_e32 v58, 0
	v_mov_b32_e32 v59, 0
	v_mov_b32_e32 v60, 0
	v_mov_b32_e32 v61, 0
	v_mov_b32_e32 v62, 0
	v_mov_b32_e32 v63, 0
	s_lshr_b32 s4, s94, 2
	s_waitcnt vmcnt(4)
	s_barrier
; __device__ __forceinline__ void qkt(f32x16& p0, f32x16& p1, const bf16* Ks, const bf16x8* qr, int r32, int hi) {
;   p0 = f32x16{}; p1 = f32x16{};
; #pragma unroll
;   for (int d0 = 0; d0 < 8; ++d0) { int cb = (d0 * 16 + hi * 8) * 2;
;     bf16x8 b0 = *reinterpret_cast<const bf16x8*>((const char*)Ks + KSWZ(r32, cb));
;     bf16x8 b1 = *reinterpret_cast<const bf16x8*>((const char*)Ks + KSWZ(32 + r32, cb));
;     p0 = __builtin_amdgcn_mfma_f32_32x32x16_bf16(b0, qr[d0], p0, 0, 0, 0);
;     p1 = __builtin_amdgcn_mfma_f32_32x32x16_bf16(b1, qr[d0], p1, 0, 0, 0); }
; }
; __device__ __forceinline__ int v_st(int k, int c) { const int kk = (k & ~0xC) | ((k & 4) << 1) | ((k & 8) >> 1); return ((kk >> 3) * 4 + (c >> 5)) * 512 + ((kk & 7) * 32 + (c & 31)) * 2; }
; __device__ __forceinline__ int v_rd_base(int lane) { return ((lane & 3) << 3) | (((lane >> 2) & 3) << 6) | (((lane >> 4) & 1) << 5) | (((lane >> 5) & 1) << 8); }
; template <int OFF> __device__ __forceinline__ s16x4 tr_read(int vb) {
;   s16x4 r; asm volatile("ds_read_b64_tr_b16 %0, %1 offset:%2" : "=&v"(r) : "v"(vb), "i"(OFF) : "memory"); return r;
; }
; template <int D0> __device__ __forceinline__ void pv_one(f32x16& od, int vb, bf16x8 pa0, bf16x8 pa1, bf16x8 pa2, bf16x8 pa3) {
;   const s16x4 l0 = tr_read<v_rd_off(D0, 0, 0)>(vb), h0 = tr_read<v_rd_off(D0, 0, 1)>(vb), l1 = tr_read<v_rd_off(D0, 1, 0)>(vb), h1 = tr_read<v_rd_off(D0, 1, 1)>(vb);
; __device__ __forceinline__ void attn_unit_fast(const bf16* __restrict__ Qb, const bf16* __restrict__ Kh, const bf16* __restrict__ Vh, bf16* __restrict__ Ob, int NT, char* lds, int t0, const float* __restrict__ qg) {
;     ...
;   for (int j = 1; j + 1 < NT; j += 2) {
;     SBAR(); qkt(pB0, pB1, (bf16*)((char*)K_lds + SHM_K), qr, r32, hi);
;     finishSM_fast(pA0, pA1, l_reg, pa0, pa1, pa2, pa3); SBAR();
;     if (j + 2 < NT) SLOAD(SO, (j + 2) * KVBLK); SBAR();
;     pv_d0(o, vb0, pa0, pa1, pa2, pa3); partialSM_fast(pB0, pB1);
;     __syncthreads(); SWAIT(); SWRITE(0, SE);
;     __syncthreads();
;     SBAR(); qkt(pA0, pA1, K_lds, qr, r32, hi);
;     if (j + 2 == NT) MASKLAST(pA0, pA1);
;     finishSM_fast(pB0, pB1, l_reg, pa0, pa1, pa2, pa3); SBAR();
;     if (j + 3 < NT) SLOAD(SE, (j + 3) * KVBLK); SBAR();
;     pv_d0(o, vb0 + (int)SHM_V, pa0, pa1, pa2, pa3); partialSM_fast(pA0, pA1);
;     __syncthreads(); SWAIT(); SWRITE(1, SO);
;     __syncthreads();
	ds_read_b128 v[206:209], v194 offset:16384
	ds_read_b128 v[210:213], v196 offset:16384
	ds_read_b128 v[214:217], v198 offset:16384
	ds_read_b128 v[218:221], v199 offset:16384
	ds_read_b128 v[160:163], v200 offset:16384
	ds_read_b128 v[164:167], v201 offset:16384
	ds_read_b128 v[168:171], v202 offset:16384
	ds_read_b128 v[172:175], v203 offset:16384
.Lattn_loop:
	s_waitcnt lgkmcnt(4)
	v_mfma_f32_32x32x16_bf16 v[96:111], v[206:209], v[112:115], 0
	ds_read_b128 v[206:209], v194 offset:24576
	v_cvt_pk_bf16_f32 v152, v64, v65
	v_cvt_pk_bf16_f32 v153, v66, v67
	v_add_f32_e32 v239, v64, v65
	v_add_f32_e32 v239, v66, v239
	v_mfma_f32_32x32x16_bf16 v[96:111], v[210:213], v[116:119], v[96:111]
	ds_read_b128 v[210:213], v196 offset:24576
	s_add_u32 m0, s5, 0x10800
	v_cvt_pk_bf16_f32 v154, v68, v69
	global_load_lds_dwordx4 v244, s[0:1]
	v_cvt_pk_bf16_f32 v155, v70, v71
	v_add_f32_e32 v239, v67, v239
	v_add_f32_e32 v239, v68, v239
	v_mfma_f32_32x32x16_bf16 v[96:111], v[214:217], v[120:123], v[96:111]
	ds_read_b128 v[214:217], v198 offset:24576
	v_add_f32_e32 v239, v69, v239
	v_add_f32_e32 v239, v70, v239
	v_mfma_f32_32x32x16_bf16 v[96:111], v[218:221], v[124:127], v[96:111]
	ds_read_b128 v[218:221], v199 offset:24576
	s_add_u32 m0, s5, 0x12800
	v_add_f32_e32 v239, v71, v239
	global_load_lds_dwordx4 v245, s[0:1]
	v_add_f32_e32 v239, v72, v239
	s_waitcnt lgkmcnt(4)
	v_mfma_f32_32x32x16_bf16 v[96:111], v[160:163], v[128:131], v[96:111]
	ds_read_b128 v[160:163], v200 offset:24576
	v_cvt_pk_bf16_f32 v156, v72, v73
	v_cvt_pk_bf16_f32 v157, v74, v75
	v_add_f32_e32 v239, v73, v239
	v_add_f32_e32 v239, v74, v239
	v_mfma_f32_32x32x16_bf16 v[96:111], v[164:167], v[132:135], v[96:111]
	ds_read_b128 v[164:167], v201 offset:24576
	v_cvt_pk_bf16_f32 v158, v76, v77
	v_cvt_pk_bf16_f32 v159, v78, v79
	v_add_f32_e32 v239, v75, v239
	v_add_f32_e32 v239, v76, v239
	v_mfma_f32_32x32x16_bf16 v[96:111], v[168:171], v[136:139], v[96:111]
	ds_read_b128 v[168:171], v202 offset:24576
	v_add_f32_e32 v239, v77, v239
	v_add_f32_e32 v239, v78, v239
	v_mfma_f32_32x32x16_bf16 v[96:111], v[172:175], v[148:151], v[96:111]
	ds_read_b128 v[172:175], v203 offset:24576
	v_add_f32_e32 v239, v79, v239
	v_add_f32_e32 v197, v239, v197
	s_waitcnt lgkmcnt(4)
	v_mfma_f32_32x32x16_bf16 v[64:79], v[206:209], v[112:115], 0
	v_mfma_f32_32x32x16_bf16 v[64:79], v[210:213], v[116:119], v[64:79]
	v_mfma_f32_32x32x16_bf16 v[64:79], v[214:217], v[120:123], v[64:79]
	ds_read_b64_tr_b16 v[222:223], v188
	ds_read_b64_tr_b16 v[224:225], v188 offset:2048
	v_mfma_f32_32x32x16_bf16 v[64:79], v[218:221], v[124:127], v[64:79]
	ds_read_b64_tr_b16 v[226:227], v188 offset:512
	ds_read_b64_tr_b16 v[228:229], v188 offset:2560
	v_exp_f32_e32 v96, v96
	v_exp_f32_e32 v97, v97
	s_waitcnt lgkmcnt(4)
	v_mfma_f32_32x32x16_bf16 v[64:79], v[160:163], v[128:131], v[64:79]
	ds_read_b64_tr_b16 v[230:231], v188 offset:1024
	ds_read_b64_tr_b16 v[232:233], v188 offset:3072
	v_exp_f32_e32 v98, v98
	v_exp_f32_e32 v99, v99
	v_exp_f32_e32 v100, v100
	v_mfma_f32_32x32x16_bf16 v[64:79], v[164:167], v[132:135], v[64:79]
	ds_read_b64_tr_b16 v[234:235], v188 offset:1536
	ds_read_b64_tr_b16 v[236:237], v188 offset:3584
	v_exp_f32_e32 v101, v101
	v_exp_f32_e32 v102, v102
	v_exp_f32_e32 v103, v103
	v_mfma_f32_32x32x16_bf16 v[64:79], v[168:171], v[136:139], v[64:79]
	ds_read_b64_tr_b16 v[240:241], v188 offset:4096
	ds_read_b64_tr_b16 v[242:243], v188 offset:6144
	v_exp_f32_e32 v104, v104
	v_exp_f32_e32 v105, v105
	v_mfma_f32_32x32x16_bf16 v[64:79], v[172:175], v[148:151], v[64:79]
	ds_read_b64_tr_b16 v[180:181], v188 offset:4608
	ds_read_b64_tr_b16 v[182:183], v188 offset:6656
	v_exp_f32_e32 v106, v106
	v_exp_f32_e32 v107, v107
	s_waitcnt lgkmcnt(6)
	v_mfma_f32_32x32x16_bf16 v[0:15], v[140:143], v[222:225], v[0:15]
	ds_read_b64_tr_b16 v[222:223], v188 offset:5120
	ds_read_b64_tr_b16 v[224:225], v188 offset:7168
	v_exp_f32_e32 v108, v108
	v_exp_f32_e32 v109, v109
	v_mfma_f32_32x32x16_bf16 v[16:31], v[140:143], v[226:229], v[16:31]
	ds_read_b64_tr_b16 v[226:227], v188 offset:5632
	ds_read_b64_tr_b16 v[228:229], v188 offset:7680
	v_exp_f32_e32 v110, v110
	v_exp_f32_e32 v111, v111
	v_mfma_f32_32x32x16_bf16 v[32:47], v[140:143], v[230:233], v[32:47]
	ds_read_b64_tr_b16 v[230:231], v188 offset:8192
	ds_read_b64_tr_b16 v[232:233], v188 offset:10240
	v_exp_f32_e32 v64, v64
	v_exp_f32_e32 v65, v65
	s_waitcnt lgkmcnt(6)
	v_mfma_f32_32x32x16_bf16 v[48:63], v[140:143], v[234:237], v[48:63]
	ds_read_b64_tr_b16 v[234:235], v188 offset:8704
	ds_read_b64_tr_b16 v[236:237], v188 offset:10752
	v_exp_f32_e32 v66, v66
	v_exp_f32_e32 v67, v67
	v_mfma_f32_32x32x16_bf16 v[0:15], v[144:147], v[240:243], v[0:15]
	ds_read_b64_tr_b16 v[240:241], v188 offset:9216
	ds_read_b64_tr_b16 v[242:243], v188 offset:11264
	v_exp_f32_e32 v68, v68
	v_exp_f32_e32 v69, v69
	v_cvt_pk_bf16_f32 v140, v96, v97
	v_cvt_pk_bf16_f32 v141, v98, v99
	v_mfma_f32_32x32x16_bf16 v[16:31], v[144:147], v[180:183], v[16:31]
	ds_read_b64_tr_b16 v[180:181], v188 offset:9728
	ds_read_b64_tr_b16 v[182:183], v188 offset:11776
	v_exp_f32_e32 v70, v70
	v_exp_f32_e32 v71, v71
	v_cvt_pk_bf16_f32 v142, v100, v101
	v_cvt_pk_bf16_f32 v143, v102, v103
	s_waitcnt lgkmcnt(6)
	v_mfma_f32_32x32x16_bf16 v[32:47], v[144:147], v[222:225], v[32:47]
	ds_read_b64_tr_b16 v[222:223], v188 offset:12288
	ds_read_b64_tr_b16 v[224:225], v188 offset:14336
	v_exp_f32_e32 v72, v72
	v_exp_f32_e32 v73, v73
	v_mfma_f32_32x32x16_bf16 v[48:63], v[144:147], v[226:229], v[48:63]
	ds_read_b64_tr_b16 v[226:227], v188 offset:12800
	ds_read_b64_tr_b16 v[228:229], v188 offset:14848
	v_exp_f32_e32 v74, v74
	v_exp_f32_e32 v75, v75
	v_mfma_f32_32x32x16_bf16 v[0:15], v[152:155], v[230:233], v[0:15]
	ds_read_b64_tr_b16 v[230:231], v188 offset:13312
	ds_read_b64_tr_b16 v[232:233], v188 offset:15360
	v_exp_f32_e32 v76, v76
	v_exp_f32_e32 v77, v77
	v_cvt_pk_bf16_f32 v144, v104, v105
	v_cvt_pk_bf16_f32 v145, v106, v107
	s_waitcnt lgkmcnt(6)
	v_mfma_f32_32x32x16_bf16 v[16:31], v[152:155], v[234:237], v[16:31]
	ds_read_b64_tr_b16 v[234:235], v188 offset:13824
	ds_read_b64_tr_b16 v[236:237], v188 offset:15872
	v_exp_f32_e32 v78, v78
	v_exp_f32_e32 v79, v79
	v_cvt_pk_bf16_f32 v146, v108, v109
	v_cvt_pk_bf16_f32 v147, v110, v111
	s_waitcnt vmcnt(6)
	s_barrier
; __device__ __forceinline__ void qkt(f32x16& p0, f32x16& p1, const bf16* Ks, const bf16x8* qr, int r32, int hi) {
;   p0 = f32x16{}; p1 = f32x16{};
; #pragma unroll
;   for (int d0 = 0; d0 < 8; ++d0) { int cb = (d0 * 16 + hi * 8) * 2;
;     bf16x8 b0 = *reinterpret_cast<const bf16x8*>((const char*)Ks + KSWZ(r32, cb));
;     bf16x8 b1 = *reinterpret_cast<const bf16x8*>((const char*)Ks + KSWZ(32 + r32, cb));
;     p0 = __builtin_amdgcn_mfma_f32_32x32x16_bf16(b0, qr[d0], p0, 0, 0, 0);
;     p1 = __builtin_amdgcn_mfma_f32_32x32x16_bf16(b1, qr[d0], p1, 0, 0, 0); }
; }
; __device__ __forceinline__ int v_st(int k, int c) { const int kk = (k & ~0xC) | ((k & 4) << 1) | ((k & 8) >> 1); return ((kk >> 3) * 4 + (c >> 5)) * 512 + ((kk & 7) * 32 + (c & 31)) * 2; }
; __device__ __forceinline__ int v_rd_base(int lane) { return ((lane & 3) << 3) | (((lane >> 2) & 3) << 6) | (((lane >> 4) & 1) << 5) | (((lane >> 5) & 1) << 8); }
; template <int OFF> __device__ __forceinline__ s16x4 tr_read(int vb) {
;   s16x4 r; asm volatile("ds_read_b64_tr_b16 %0, %1 offset:%2" : "=&v"(r) : "v"(vb), "i"(OFF) : "memory"); return r;
; }
; template <int D0> __device__ __forceinline__ void pv_one(f32x16& od, int vb, bf16x8 pa0, bf16x8 pa1, bf16x8 pa2, bf16x8 pa3) {
;   const s16x4 l0 = tr_read<v_rd_off(D0, 0, 0)>(vb), h0 = tr_read<v_rd_off(D0, 0, 1)>(vb), l1 = tr_read<v_rd_off(D0, 1, 0)>(vb), h1 = tr_read<v_rd_off(D0, 1, 1)>(vb);
; __device__ __forceinline__ void attn_unit_fast(const bf16* __restrict__ Qb, const bf16* __restrict__ Kh, const bf16* __restrict__ Vh, bf16* __restrict__ Ob, int NT, char* lds, int t0, const float* __restrict__ qg) {
;     ...
;   for (int j = 1; j + 1 < NT; j += 2) {
;     SBAR(); qkt(pB0, pB1, (bf16*)((char*)K_lds + SHM_K), qr, r32, hi);
;     finishSM_fast(pA0, pA1, l_reg, pa0, pa1, pa2, pa3); SBAR();
;     if (j + 2 < NT) SLOAD(SO, (j + 2) * KVBLK); SBAR();
;     pv_d0(o, vb0, pa0, pa1, pa2, pa3); partialSM_fast(pB0, pB1);
;     __syncthreads(); SWAIT(); SWRITE(0, SE);
;     __syncthreads();
;     SBAR(); qkt(pA0, pA1, K_lds, qr, r32, hi);
;     if (j + 2 == NT) MASKLAST(pA0, pA1);
;     finishSM_fast(pB0, pB1, l_reg, pa0, pa1, pa2, pa3); SBAR();
;     if (j + 3 < NT) SLOAD(SE, (j + 3) * KVBLK); SBAR();
;     pv_d0(o, vb0 + (int)SHM_V, pa0, pa1, pa2, pa3); partialSM_fast(pA0, pA1);
;     __syncthreads(); SWAIT(); SWRITE(1, SO);
;     __syncthreads();
	v_mfma_f32_32x32x16_bf16 v[32:47], v[152:155], v[240:243], v[32:47]
	s_add_u32 m0, s5, 0xc000
	v_add_f32_e32 v238, v96, v97
	global_load_lds_dwordx4 v253, s[0:1]
	v_add_f32_e32 v238, v98, v238
	v_add_f32_e32 v238, v99, v238
	v_mfma_f32_32x32x16_bf16 v[48:63], v[152:155], v[180:183], v[48:63]
	s_add_u32 m0, s5, 0xe000
	v_add_f32_e32 v238, v100, v238
	global_load_lds_dwordx4 v254, s[0:1]
	v_add_f32_e32 v238, v101, v238
	v_add_f32_e32 v238, v102, v238
	s_add_u32 s0, s0, 0x4000
	s_addc_u32 s1, s1, 0
	s_waitcnt lgkmcnt(2)
	v_mfma_f32_32x32x16_bf16 v[0:15], v[156:159], v[222:225], v[0:15]
	v_add_f32_e32 v238, v103, v238
	v_add_f32_e32 v238, v104, v238
	v_add_f32_e32 v238, v105, v238
	ds_read_b128 v[206:209], v194 offset:32768
	ds_read_b128 v[210:213], v196 offset:32768
	v_mfma_f32_32x32x16_bf16 v[16:31], v[156:159], v[226:229], v[16:31]
	v_add_f32_e32 v238, v106, v238
	v_add_f32_e32 v238, v107, v238
	v_add_f32_e32 v238, v108, v238
	ds_read_b128 v[214:217], v198 offset:32768
	ds_read_b128 v[218:221], v199 offset:32768
	v_mfma_f32_32x32x16_bf16 v[32:47], v[156:159], v[230:233], v[32:47]
	v_add_f32_e32 v238, v109, v238
	v_add_f32_e32 v238, v110, v238
	ds_read_b128 v[160:163], v200 offset:32768
	ds_read_b128 v[164:167], v201 offset:32768
	s_waitcnt lgkmcnt(6)
	v_mfma_f32_32x32x16_bf16 v[48:63], v[156:159], v[234:237], v[48:63]
	v_add_f32_e32 v238, v111, v238
	v_add_f32_e32 v197, v238, v197
	ds_read_b128 v[168:171], v202 offset:32768
	ds_read_b128 v[172:175], v203 offset:32768
	s_waitcnt lgkmcnt(4)
	v_mfma_f32_32x32x16_bf16 v[96:111], v[206:209], v[112:115], 0
	ds_read_b128 v[206:209], v194 offset:40960
	v_cvt_pk_bf16_f32 v152, v64, v65
	v_cvt_pk_bf16_f32 v153, v66, v67
	v_add_f32_e32 v239, v64, v65
	v_add_f32_e32 v239, v66, v239
	v_mfma_f32_32x32x16_bf16 v[96:111], v[210:213], v[116:119], v[96:111]
	ds_read_b128 v[210:213], v196 offset:40960
	s_add_u32 m0, s5, 0x14800
	v_cvt_pk_bf16_f32 v154, v68, v69
	global_load_lds_dwordx4 v244, s[0:1]
	v_cvt_pk_bf16_f32 v155, v70, v71
	v_add_f32_e32 v239, v67, v239
	v_add_f32_e32 v239, v68, v239
	v_mfma_f32_32x32x16_bf16 v[96:111], v[214:217], v[120:123], v[96:111]
	ds_read_b128 v[214:217], v198 offset:40960
	v_add_f32_e32 v239, v69, v239
	v_add_f32_e32 v239, v70, v239
	v_mfma_f32_32x32x16_bf16 v[96:111], v[218:221], v[124:127], v[96:111]
	ds_read_b128 v[218:221], v199 offset:40960
	s_add_u32 m0, s5, 0x16800
	v_add_f32_e32 v239, v71, v239
	global_load_lds_dwordx4 v245, s[0:1]
	v_add_f32_e32 v239, v72, v239
	s_waitcnt lgkmcnt(4)
	v_mfma_f32_32x32x16_bf16 v[96:111], v[160:163], v[128:131], v[96:111]
	ds_read_b128 v[160:163], v200 offset:40960
	v_cvt_pk_bf16_f32 v156, v72, v73
	v_cvt_pk_bf16_f32 v157, v74, v75
	v_add_f32_e32 v239, v73, v239
	v_add_f32_e32 v239, v74, v239
	v_mfma_f32_32x32x16_bf16 v[96:111], v[164:167], v[132:135], v[96:111]
	ds_read_b128 v[164:167], v201 offset:40960
	v_cvt_pk_bf16_f32 v158, v76, v77
	v_cvt_pk_bf16_f32 v159, v78, v79
	v_add_f32_e32 v239, v75, v239
	v_add_f32_e32 v239, v76, v239
	v_mfma_f32_32x32x16_bf16 v[96:111], v[168:171], v[136:139], v[96:111]
	ds_read_b128 v[168:171], v202 offset:40960
	v_add_f32_e32 v239, v77, v239
	v_add_f32_e32 v239, v78, v239
	v_mfma_f32_32x32x16_bf16 v[96:111], v[172:175], v[148:151], v[96:111]
	ds_read_b128 v[172:175], v203 offset:40960
	v_add_f32_e32 v239, v79, v239
	v_add_f32_e32 v197, v239, v197
	s_waitcnt lgkmcnt(4)
	v_mfma_f32_32x32x16_bf16 v[64:79], v[206:209], v[112:115], 0
	v_mfma_f32_32x32x16_bf16 v[64:79], v[210:213], v[116:119], v[64:79]
	v_mfma_f32_32x32x16_bf16 v[64:79], v[214:217], v[120:123], v[64:79]
	ds_read_b64_tr_b16 v[222:223], v188 offset:16384
	ds_read_b64_tr_b16 v[224:225], v188 offset:18432
	v_mfma_f32_32x32x16_bf16 v[64:79], v[218:221], v[124:127], v[64:79]
	ds_read_b64_tr_b16 v[226:227], v188 offset:16896
	ds_read_b64_tr_b16 v[228:229], v188 offset:18944
	v_exp_f32_e32 v96, v96
	v_exp_f32_e32 v97, v97
	s_waitcnt lgkmcnt(4)
	v_mfma_f32_32x32x16_bf16 v[64:79], v[160:163], v[128:131], v[64:79]
	ds_read_b64_tr_b16 v[230:231], v188 offset:17408
	ds_read_b64_tr_b16 v[232:233], v188 offset:19456
	v_exp_f32_e32 v98, v98
	v_exp_f32_e32 v99, v99
	v_exp_f32_e32 v100, v100
	v_mfma_f32_32x32x16_bf16 v[64:79], v[164:167], v[132:135], v[64:79]
	ds_read_b64_tr_b16 v[234:235], v188 offset:17920
	ds_read_b64_tr_b16 v[236:237], v188 offset:19968
	v_exp_f32_e32 v101, v101
	v_exp_f32_e32 v102, v102
	v_exp_f32_e32 v103, v103
	v_mfma_f32_32x32x16_bf16 v[64:79], v[168:171], v[136:139], v[64:79]
	ds_read_b64_tr_b16 v[240:241], v188 offset:20480
	ds_read_b64_tr_b16 v[242:243], v188 offset:22528
	v_exp_f32_e32 v104, v104
	v_exp_f32_e32 v105, v105
	v_mfma_f32_32x32x16_bf16 v[64:79], v[172:175], v[148:151], v[64:79]
	ds_read_b64_tr_b16 v[180:181], v188 offset:20992
	ds_read_b64_tr_b16 v[182:183], v188 offset:23040
	v_exp_f32_e32 v106, v106
	v_exp_f32_e32 v107, v107
	s_waitcnt lgkmcnt(6)
	v_mfma_f32_32x32x16_bf16 v[0:15], v[140:143], v[222:225], v[0:15]
	ds_read_b64_tr_b16 v[222:223], v188 offset:21504
	ds_read_b64_tr_b16 v[224:225], v188 offset:23552
	v_exp_f32_e32 v108, v108
	v_exp_f32_e32 v109, v109
	v_mfma_f32_32x32x16_bf16 v[16:31], v[140:143], v[226:229], v[16:31]
	ds_read_b64_tr_b16 v[226:227], v188 offset:22016
	ds_read_b64_tr_b16 v[228:229], v188 offset:24064
	v_exp_f32_e32 v110, v110
	v_exp_f32_e32 v111, v111
	v_mfma_f32_32x32x16_bf16 v[32:47], v[140:143], v[230:233], v[32:47]
	ds_read_b64_tr_b16 v[230:231], v188 offset:24576
	ds_read_b64_tr_b16 v[232:233], v188 offset:26624
	v_exp_f32_e32 v64, v64
	v_exp_f32_e32 v65, v65
	s_waitcnt lgkmcnt(6)
; __device__ __forceinline__ void qkt(f32x16& p0, f32x16& p1, const bf16* Ks, const bf16x8* qr, int r32, int hi) {
;   p0 = f32x16{}; p1 = f32x16{};
; #pragma unroll
;   for (int d0 = 0; d0 < 8; ++d0) { int cb = (d0 * 16 + hi * 8) * 2;
;     bf16x8 b0 = *reinterpret_cast<const bf16x8*>((const char*)Ks + KSWZ(r32, cb));
;     bf16x8 b1 = *reinterpret_cast<const bf16x8*>((const char*)Ks + KSWZ(32 + r32, cb));
;     p0 = __builtin_amdgcn_mfma_f32_32x32x16_bf16(b0, qr[d0], p0, 0, 0, 0);
;     p1 = __builtin_amdgcn_mfma_f32_32x32x16_bf16(b1, qr[d0], p1, 0, 0, 0); }
; }
; __device__ __forceinline__ int v_st(int k, int c) { const int kk = (k & ~0xC) | ((k & 4) << 1) | ((k & 8) >> 1); return ((kk >> 3) * 4 + (c >> 5)) * 512 + ((kk & 7) * 32 + (c & 31)) * 2; }
; __device__ __forceinline__ int v_rd_base(int lane) { return ((lane & 3) << 3) | (((lane >> 2) & 3) << 6) | (((lane >> 4) & 1) << 5) | (((lane >> 5) & 1) << 8); }
; template <int OFF> __device__ __forceinline__ s16x4 tr_read(int vb) {
;   s16x4 r; asm volatile("ds_read_b64_tr_b16 %0, %1 offset:%2" : "=&v"(r) : "v"(vb), "i"(OFF) : "memory"); return r;
; }
; template <int D0> __device__ __forceinline__ void pv_one(f32x16& od, int vb, bf16x8 pa0, bf16x8 pa1, bf16x8 pa2, bf16x8 pa3) {
;   const s16x4 l0 = tr_read<v_rd_off(D0, 0, 0)>(vb), h0 = tr_read<v_rd_off(D0, 0, 1)>(vb), l1 = tr_read<v_rd_off(D0, 1, 0)>(vb), h1 = tr_read<v_rd_off(D0, 1, 1)>(vb);
; __device__ __forceinline__ void attn_unit_fast(const bf16* __restrict__ Qb, const bf16* __restrict__ Kh, const bf16* __restrict__ Vh, bf16* __restrict__ Ob, int NT, char* lds, int t0, const float* __restrict__ qg) {
;     ...
;   for (int j = 1; j + 1 < NT; j += 2) {
;     SBAR(); qkt(pB0, pB1, (bf16*)((char*)K_lds + SHM_K), qr, r32, hi);
;     finishSM_fast(pA0, pA1, l_reg, pa0, pa1, pa2, pa3); SBAR();
;     if (j + 2 < NT) SLOAD(SO, (j + 2) * KVBLK); SBAR();
;     pv_d0(o, vb0, pa0, pa1, pa2, pa3); partialSM_fast(pB0, pB1);
;     __syncthreads(); SWAIT(); SWRITE(0, SE);
;     __syncthreads();
;     SBAR(); qkt(pA0, pA1, K_lds, qr, r32, hi);
;     if (j + 2 == NT) MASKLAST(pA0, pA1);
;     finishSM_fast(pB0, pB1, l_reg, pa0, pa1, pa2, pa3); SBAR();
;     if (j + 3 < NT) SLOAD(SE, (j + 3) * KVBLK); SBAR();
;     pv_d0(o, vb0 + (int)SHM_V, pa0, pa1, pa2, pa3); partialSM_fast(pA0, pA1);
;     __syncthreads(); SWAIT(); SWRITE(1, SO);
;     __syncthreads();
	v_mfma_f32_32x32x16_bf16 v[48:63], v[140:143], v[234:237], v[48:63]
	ds_read_b64_tr_b16 v[234:235], v188 offset:25088
	ds_read_b64_tr_b16 v[236:237], v188 offset:27136
	v_exp_f32_e32 v66, v66
	v_exp_f32_e32 v67, v67
	v_mfma_f32_32x32x16_bf16 v[0:15], v[144:147], v[240:243], v[0:15]
	ds_read_b64_tr_b16 v[240:241], v188 offset:25600
	ds_read_b64_tr_b16 v[242:243], v188 offset:27648
	v_exp_f32_e32 v68, v68
	v_exp_f32_e32 v69, v69
	v_cvt_pk_bf16_f32 v140, v96, v97
	v_cvt_pk_bf16_f32 v141, v98, v99
	v_mfma_f32_32x32x16_bf16 v[16:31], v[144:147], v[180:183], v[16:31]
	ds_read_b64_tr_b16 v[180:181], v188 offset:26112
	ds_read_b64_tr_b16 v[182:183], v188 offset:28160
	v_exp_f32_e32 v70, v70
	v_exp_f32_e32 v71, v71
	v_cvt_pk_bf16_f32 v142, v100, v101
	v_cvt_pk_bf16_f32 v143, v102, v103
	s_waitcnt lgkmcnt(6)
	v_mfma_f32_32x32x16_bf16 v[32:47], v[144:147], v[222:225], v[32:47]
	ds_read_b64_tr_b16 v[222:223], v188 offset:28672
	ds_read_b64_tr_b16 v[224:225], v188 offset:30720
	v_exp_f32_e32 v72, v72
	v_exp_f32_e32 v73, v73
	v_mfma_f32_32x32x16_bf16 v[48:63], v[144:147], v[226:229], v[48:63]
	ds_read_b64_tr_b16 v[226:227], v188 offset:29184
	ds_read_b64_tr_b16 v[228:229], v188 offset:31232
	v_exp_f32_e32 v74, v74
	v_exp_f32_e32 v75, v75
	v_mfma_f32_32x32x16_bf16 v[0:15], v[152:155], v[230:233], v[0:15]
	ds_read_b64_tr_b16 v[230:231], v188 offset:29696
	ds_read_b64_tr_b16 v[232:233], v188 offset:31744
	v_exp_f32_e32 v76, v76
	v_exp_f32_e32 v77, v77
	v_cvt_pk_bf16_f32 v144, v104, v105
	v_cvt_pk_bf16_f32 v145, v106, v107
	s_waitcnt lgkmcnt(6)
	v_mfma_f32_32x32x16_bf16 v[16:31], v[152:155], v[234:237], v[16:31]
	ds_read_b64_tr_b16 v[234:235], v188 offset:30208
	ds_read_b64_tr_b16 v[236:237], v188 offset:32256
	v_exp_f32_e32 v78, v78
	v_exp_f32_e32 v79, v79
	v_cvt_pk_bf16_f32 v146, v108, v109
	v_cvt_pk_bf16_f32 v147, v110, v111
	s_waitcnt vmcnt(6)
	s_barrier
	v_mfma_f32_32x32x16_bf16 v[32:47], v[152:155], v[240:243], v[32:47]
	s_add_u32 m0, s5, 0x0
	v_add_f32_e32 v238, v96, v97
	global_load_lds_dwordx4 v253, s[0:1]
	v_add_f32_e32 v238, v98, v238
	v_add_f32_e32 v238, v99, v238
	v_mfma_f32_32x32x16_bf16 v[48:63], v[152:155], v[180:183], v[48:63]
	s_add_u32 m0, s5, 0x2000
	v_add_f32_e32 v238, v100, v238
	global_load_lds_dwordx4 v254, s[0:1]
	v_add_f32_e32 v238, v101, v238
	v_add_f32_e32 v238, v102, v238
	s_add_u32 s0, s0, 0x4000
	s_addc_u32 s1, s1, 0
	s_waitcnt lgkmcnt(2)
	v_mfma_f32_32x32x16_bf16 v[0:15], v[156:159], v[222:225], v[0:15]
	v_add_f32_e32 v238, v103, v238
	v_add_f32_e32 v238, v104, v238
	v_add_f32_e32 v238, v105, v238
	ds_read_b128 v[206:209], v194 offset:49152
	ds_read_b128 v[210:213], v196 offset:49152
	v_mfma_f32_32x32x16_bf16 v[16:31], v[156:159], v[226:229], v[16:31]
	v_add_f32_e32 v238, v106, v238
	v_add_f32_e32 v238, v107, v238
	v_add_f32_e32 v238, v108, v238
	ds_read_b128 v[214:217], v198 offset:49152
	ds_read_b128 v[218:221], v199 offset:49152
	v_mfma_f32_32x32x16_bf16 v[32:47], v[156:159], v[230:233], v[32:47]
	v_add_f32_e32 v238, v109, v238
	v_add_f32_e32 v238, v110, v238
	ds_read_b128 v[160:163], v200 offset:49152
	ds_read_b128 v[164:167], v201 offset:49152
	s_waitcnt lgkmcnt(6)
	v_mfma_f32_32x32x16_bf16 v[48:63], v[156:159], v[234:237], v[48:63]
	v_add_f32_e32 v238, v111, v238
	v_add_f32_e32 v197, v238, v197
	ds_read_b128 v[168:171], v202 offset:49152
	ds_read_b128 v[172:175], v203 offset:49152
	s_waitcnt lgkmcnt(4)
	v_mfma_f32_32x32x16_bf16 v[96:111], v[206:209], v[112:115], 0
	ds_read_b128 v[206:209], v194 offset:57344
	v_cvt_pk_bf16_f32 v152, v64, v65
	v_cvt_pk_bf16_f32 v153, v66, v67
	v_add_f32_e32 v239, v64, v65
	v_add_f32_e32 v239, v66, v239
	v_mfma_f32_32x32x16_bf16 v[96:111], v[210:213], v[116:119], v[96:111]
	ds_read_b128 v[210:213], v196 offset:57344
	s_add_u32 m0, s5, 0x18800
	v_cvt_pk_bf16_f32 v154, v68, v69
	global_load_lds_dwordx4 v244, s[0:1]
	v_cvt_pk_bf16_f32 v155, v70, v71
	v_add_f32_e32 v239, v67, v239
	v_add_f32_e32 v239, v68, v239
	v_mfma_f32_32x32x16_bf16 v[96:111], v[214:217], v[120:123], v[96:111]
	ds_read_b128 v[214:217], v198 offset:57344
	v_add_f32_e32 v239, v69, v239
	v_add_f32_e32 v239, v70, v239
	v_mfma_f32_32x32x16_bf16 v[96:111], v[218:221], v[124:127], v[96:111]
	ds_read_b128 v[218:221], v199 offset:57344
	s_add_u32 m0, s5, 0x1a800
	v_add_f32_e32 v239, v71, v239
	global_load_lds_dwordx4 v245, s[0:1]
	v_add_f32_e32 v239, v72, v239
	s_waitcnt lgkmcnt(4)
	v_mfma_f32_32x32x16_bf16 v[96:111], v[160:163], v[128:131], v[96:111]
	ds_read_b128 v[160:163], v200 offset:57344
	v_cvt_pk_bf16_f32 v156, v72, v73
	v_cvt_pk_bf16_f32 v157, v74, v75
	v_add_f32_e32 v239, v73, v239
	v_add_f32_e32 v239, v74, v239
	v_mfma_f32_32x32x16_bf16 v[96:111], v[164:167], v[132:135], v[96:111]
	ds_read_b128 v[164:167], v201 offset:57344
	v_cvt_pk_bf16_f32 v158, v76, v77
	v_cvt_pk_bf16_f32 v159, v78, v79
	v_add_f32_e32 v239, v75, v239
	v_add_f32_e32 v239, v76, v239
	v_mfma_f32_32x32x16_bf16 v[96:111], v[168:171], v[136:139], v[96:111]
	ds_read_b128 v[168:171], v202 offset:57344
	v_add_f32_e32 v239, v77, v239
	v_add_f32_e32 v239, v78, v239
	v_mfma_f32_32x32x16_bf16 v[96:111], v[172:175], v[148:151], v[96:111]
	ds_read_b128 v[172:175], v203 offset:57344
	v_add_f32_e32 v239, v79, v239
	v_add_f32_e32 v197, v239, v197
	s_waitcnt lgkmcnt(4)
	v_mfma_f32_32x32x16_bf16 v[64:79], v[206:209], v[112:115], 0
	v_mfma_f32_32x32x16_bf16 v[64:79], v[210:213], v[116:119], v[64:79]
	v_mfma_f32_32x32x16_bf16 v[64:79], v[214:217], v[120:123], v[64:79]
	ds_read_b64_tr_b16 v[222:223], v188 offset:32768
	ds_read_b64_tr_b16 v[224:225], v188 offset:34816
	v_mfma_f32_32x32x16_bf16 v[64:79], v[218:221], v[124:127], v[64:79]
	ds_read_b64_tr_b16 v[226:227], v188 offset:33280
	ds_read_b64_tr_b16 v[228:229], v188 offset:35328
	v_exp_f32_e32 v96, v96
	v_exp_f32_e32 v97, v97
	s_waitcnt lgkmcnt(4)
; __device__ __forceinline__ void qkt(f32x16& p0, f32x16& p1, const bf16* Ks, const bf16x8* qr, int r32, int hi) {
;   p0 = f32x16{}; p1 = f32x16{};
; #pragma unroll
;   for (int d0 = 0; d0 < 8; ++d0) { int cb = (d0 * 16 + hi * 8) * 2;
;     bf16x8 b0 = *reinterpret_cast<const bf16x8*>((const char*)Ks + KSWZ(r32, cb));
;     bf16x8 b1 = *reinterpret_cast<const bf16x8*>((const char*)Ks + KSWZ(32 + r32, cb));
;     p0 = __builtin_amdgcn_mfma_f32_32x32x16_bf16(b0, qr[d0], p0, 0, 0, 0);
;     p1 = __builtin_amdgcn_mfma_f32_32x32x16_bf16(b1, qr[d0], p1, 0, 0, 0); }
; }
; __device__ __forceinline__ int v_st(int k, int c) { const int kk = (k & ~0xC) | ((k & 4) << 1) | ((k & 8) >> 1); return ((kk >> 3) * 4 + (c >> 5)) * 512 + ((kk & 7) * 32 + (c & 31)) * 2; }
; __device__ __forceinline__ int v_rd_base(int lane) { return ((lane & 3) << 3) | (((lane >> 2) & 3) << 6) | (((lane >> 4) & 1) << 5) | (((lane >> 5) & 1) << 8); }
; template <int OFF> __device__ __forceinline__ s16x4 tr_read(int vb) {
;   s16x4 r; asm volatile("ds_read_b64_tr_b16 %0, %1 offset:%2" : "=&v"(r) : "v"(vb), "i"(OFF) : "memory"); return r;
; }
; template <int D0> __device__ __forceinline__ void pv_one(f32x16& od, int vb, bf16x8 pa0, bf16x8 pa1, bf16x8 pa2, bf16x8 pa3) {
;   const s16x4 l0 = tr_read<v_rd_off(D0, 0, 0)>(vb), h0 = tr_read<v_rd_off(D0, 0, 1)>(vb), l1 = tr_read<v_rd_off(D0, 1, 0)>(vb), h1 = tr_read<v_rd_off(D0, 1, 1)>(vb);
;   const s16x4 l2 = tr_read<v_rd_off(D0, 2, 0)>(vb), h2 = tr_read<v_rd_off(D0, 2, 1)>(vb), l3 = tr_read<v_rd_off(D0, 3, 0)>(vb), h3 = tr_read<v_rd_off(D0, 3, 1)>(vb);
;   asm volatile("s_waitcnt lgkmcnt(0)" ::: "memory"); SBAR();
;     ...
;   od = __builtin_amdgcn_mfma_f32_32x32x16_bf16(pa0, PK(l0, h0), od, 0, 0, 0);
;   od = __builtin_amdgcn_mfma_f32_32x32x16_bf16(pa1, PK(l1, h1), od, 0, 0, 0);
;   od = __builtin_amdgcn_mfma_f32_32x32x16_bf16(pa2, PK(l2, h2), od, 0, 0, 0);
;   od = __builtin_amdgcn_mfma_f32_32x32x16_bf16(pa3, PK(l3, h3), od, 0, 0, 0);
;     ...
; }
; __device__ __forceinline__ void partialSM_fast(f32x16& p0, f32x16& p1) {
; #pragma unroll
;   for (int r = 0; r < 16; ++r) p0[r] = __builtin_amdgcn_exp2f(p0[r]);
; }
; __device__ __forceinline__ void finishSM_fast(f32x16& p0, f32x16& p1, float& l_reg, bf16x8& pa0, bf16x8& pa1, bf16x8& pa2, bf16x8& pa3) {
; #pragma unroll
;   for (int r = 0; r < 16; ++r) p1[r] = __builtin_amdgcn_exp2f(p1[r]);
;   float ps = 0;
	v_mfma_f32_32x32x16_bf16 v[64:79], v[160:163], v[128:131], v[64:79]
	ds_read_b64_tr_b16 v[230:231], v188 offset:33792
	ds_read_b64_tr_b16 v[232:233], v188 offset:35840
	v_exp_f32_e32 v98, v98
	v_exp_f32_e32 v99, v99
	v_exp_f32_e32 v100, v100
	v_mfma_f32_32x32x16_bf16 v[64:79], v[164:167], v[132:135], v[64:79]
	ds_read_b64_tr_b16 v[234:235], v188 offset:34304
	ds_read_b64_tr_b16 v[236:237], v188 offset:36352
	v_exp_f32_e32 v101, v101
	v_exp_f32_e32 v102, v102
	v_exp_f32_e32 v103, v103
	v_mfma_f32_32x32x16_bf16 v[64:79], v[168:171], v[136:139], v[64:79]
	ds_read_b64_tr_b16 v[240:241], v188 offset:36864
	ds_read_b64_tr_b16 v[242:243], v188 offset:38912
	v_exp_f32_e32 v104, v104
	v_exp_f32_e32 v105, v105
	v_mfma_f32_32x32x16_bf16 v[64:79], v[172:175], v[148:151], v[64:79]
	ds_read_b64_tr_b16 v[180:181], v188 offset:37376
	ds_read_b64_tr_b16 v[182:183], v188 offset:39424
	v_exp_f32_e32 v106, v106
	v_exp_f32_e32 v107, v107
	s_waitcnt lgkmcnt(6)
	v_mfma_f32_32x32x16_bf16 v[0:15], v[140:143], v[222:225], v[0:15]
	ds_read_b64_tr_b16 v[222:223], v188 offset:37888
	ds_read_b64_tr_b16 v[224:225], v188 offset:39936
	v_exp_f32_e32 v108, v108
	v_exp_f32_e32 v109, v109
	v_mfma_f32_32x32x16_bf16 v[16:31], v[140:143], v[226:229], v[16:31]
	ds_read_b64_tr_b16 v[226:227], v188 offset:38400
	ds_read_b64_tr_b16 v[228:229], v188 offset:40448
	v_exp_f32_e32 v110, v110
	v_exp_f32_e32 v111, v111
	v_mfma_f32_32x32x16_bf16 v[32:47], v[140:143], v[230:233], v[32:47]
	ds_read_b64_tr_b16 v[230:231], v188 offset:40960
	ds_read_b64_tr_b16 v[232:233], v188 offset:43008
	v_exp_f32_e32 v64, v64
	v_exp_f32_e32 v65, v65
	s_waitcnt lgkmcnt(6)
	v_mfma_f32_32x32x16_bf16 v[48:63], v[140:143], v[234:237], v[48:63]
	ds_read_b64_tr_b16 v[234:235], v188 offset:41472
	ds_read_b64_tr_b16 v[236:237], v188 offset:43520
	v_exp_f32_e32 v66, v66
	v_exp_f32_e32 v67, v67
	v_mfma_f32_32x32x16_bf16 v[0:15], v[144:147], v[240:243], v[0:15]
	ds_read_b64_tr_b16 v[240:241], v188 offset:41984
	ds_read_b64_tr_b16 v[242:243], v188 offset:44032
	v_exp_f32_e32 v68, v68
	v_exp_f32_e32 v69, v69
	v_cvt_pk_bf16_f32 v140, v96, v97
	v_cvt_pk_bf16_f32 v141, v98, v99
	v_mfma_f32_32x32x16_bf16 v[16:31], v[144:147], v[180:183], v[16:31]
	ds_read_b64_tr_b16 v[180:181], v188 offset:42496
	ds_read_b64_tr_b16 v[182:183], v188 offset:44544
	v_exp_f32_e32 v70, v70
	v_exp_f32_e32 v71, v71
	v_cvt_pk_bf16_f32 v142, v100, v101
	v_cvt_pk_bf16_f32 v143, v102, v103
	s_waitcnt lgkmcnt(6)
	v_mfma_f32_32x32x16_bf16 v[32:47], v[144:147], v[222:225], v[32:47]
	ds_read_b64_tr_b16 v[222:223], v188 offset:45056
	ds_read_b64_tr_b16 v[224:225], v188 offset:47104
	v_exp_f32_e32 v72, v72
	v_exp_f32_e32 v73, v73
	v_mfma_f32_32x32x16_bf16 v[48:63], v[144:147], v[226:229], v[48:63]
	ds_read_b64_tr_b16 v[226:227], v188 offset:45568
	ds_read_b64_tr_b16 v[228:229], v188 offset:47616
	v_exp_f32_e32 v74, v74
	v_exp_f32_e32 v75, v75
	v_mfma_f32_32x32x16_bf16 v[0:15], v[152:155], v[230:233], v[0:15]
	ds_read_b64_tr_b16 v[230:231], v188 offset:46080
	ds_read_b64_tr_b16 v[232:233], v188 offset:48128
	v_exp_f32_e32 v76, v76
	v_exp_f32_e32 v77, v77
	v_cvt_pk_bf16_f32 v144, v104, v105
	v_cvt_pk_bf16_f32 v145, v106, v107
	s_waitcnt lgkmcnt(6)
	v_mfma_f32_32x32x16_bf16 v[16:31], v[152:155], v[234:237], v[16:31]
	ds_read_b64_tr_b16 v[234:235], v188 offset:46592
	ds_read_b64_tr_b16 v[236:237], v188 offset:48640
	v_exp_f32_e32 v78, v78
	v_exp_f32_e32 v79, v79
	v_cvt_pk_bf16_f32 v146, v108, v109
	v_cvt_pk_bf16_f32 v147, v110, v111
	s_waitcnt vmcnt(6)
	s_barrier
	v_mfma_f32_32x32x16_bf16 v[32:47], v[152:155], v[240:243], v[32:47]
	s_add_u32 m0, s5, 0x4000
	v_add_f32_e32 v238, v96, v97
	global_load_lds_dwordx4 v253, s[0:1]
	v_add_f32_e32 v238, v98, v238
	v_add_f32_e32 v238, v99, v238
	v_mfma_f32_32x32x16_bf16 v[48:63], v[152:155], v[180:183], v[48:63]
	s_add_u32 m0, s5, 0x6000
	v_add_f32_e32 v238, v100, v238
	global_load_lds_dwordx4 v254, s[0:1]
	v_add_f32_e32 v238, v101, v238
	v_add_f32_e32 v238, v102, v238
	s_add_u32 s0, s0, 0x4000
	s_addc_u32 s1, s1, 0
	s_waitcnt lgkmcnt(2)
	v_mfma_f32_32x32x16_bf16 v[0:15], v[156:159], v[222:225], v[0:15]
	v_add_f32_e32 v238, v103, v238
	v_add_f32_e32 v238, v104, v238
	v_add_f32_e32 v238, v105, v238
	ds_read_b128 v[206:209], v194
	ds_read_b128 v[210:213], v196
	v_mfma_f32_32x32x16_bf16 v[16:31], v[156:159], v[226:229], v[16:31]
	v_add_f32_e32 v238, v106, v238
	v_add_f32_e32 v238, v107, v238
	v_add_f32_e32 v238, v108, v238
	ds_read_b128 v[214:217], v198
	ds_read_b128 v[218:221], v199
	v_mfma_f32_32x32x16_bf16 v[32:47], v[156:159], v[230:233], v[32:47]
	v_add_f32_e32 v238, v109, v238
	v_add_f32_e32 v238, v110, v238
	ds_read_b128 v[160:163], v200
	ds_read_b128 v[164:167], v201
	s_waitcnt lgkmcnt(6)
	v_mfma_f32_32x32x16_bf16 v[48:63], v[156:159], v[234:237], v[48:63]
	v_add_f32_e32 v238, v111, v238
	v_add_f32_e32 v197, v238, v197
	ds_read_b128 v[168:171], v202
	ds_read_b128 v[172:175], v203
	s_waitcnt lgkmcnt(4)
	v_mfma_f32_32x32x16_bf16 v[96:111], v[206:209], v[112:115], 0
	ds_read_b128 v[206:209], v194 offset:8192
	v_cvt_pk_bf16_f32 v152, v64, v65
	v_cvt_pk_bf16_f32 v153, v66, v67
	v_add_f32_e32 v239, v64, v65
	v_add_f32_e32 v239, v66, v239
	v_mfma_f32_32x32x16_bf16 v[96:111], v[210:213], v[116:119], v[96:111]
	ds_read_b128 v[210:213], v196 offset:8192
	s_add_u32 m0, s5, 0x1c800
	v_cvt_pk_bf16_f32 v154, v68, v69
	global_load_lds_dwordx4 v244, s[0:1]
	v_cvt_pk_bf16_f32 v155, v70, v71
	v_add_f32_e32 v239, v67, v239
	v_add_f32_e32 v239, v68, v239
	v_mfma_f32_32x32x16_bf16 v[96:111], v[214:217], v[120:123], v[96:111]
	ds_read_b128 v[214:217], v198 offset:8192
	v_add_f32_e32 v239, v69, v239
	v_add_f32_e32 v239, v70, v239
	v_mfma_f32_32x32x16_bf16 v[96:111], v[218:221], v[124:127], v[96:111]
	ds_read_b128 v[218:221], v199 offset:8192
	s_add_u32 m0, s5, 0x1e800
	v_add_f32_e32 v239, v71, v239
	global_load_lds_dwordx4 v245, s[0:1]
	v_add_f32_e32 v239, v72, v239
	s_waitcnt lgkmcnt(4)
; __device__ __forceinline__ void qkt(f32x16& p0, f32x16& p1, const bf16* Ks, const bf16x8* qr, int r32, int hi) {
;   p0 = f32x16{}; p1 = f32x16{};
; #pragma unroll
;   for (int d0 = 0; d0 < 8; ++d0) { int cb = (d0 * 16 + hi * 8) * 2;
;     bf16x8 b0 = *reinterpret_cast<const bf16x8*>((const char*)Ks + KSWZ(r32, cb));
;     bf16x8 b1 = *reinterpret_cast<const bf16x8*>((const char*)Ks + KSWZ(32 + r32, cb));
;     p0 = __builtin_amdgcn_mfma_f32_32x32x16_bf16(b0, qr[d0], p0, 0, 0, 0);
;     p1 = __builtin_amdgcn_mfma_f32_32x32x16_bf16(b1, qr[d0], p1, 0, 0, 0); }
; }
; __device__ __forceinline__ int v_st(int k, int c) { const int kk = (k & ~0xC) | ((k & 4) << 1) | ((k & 8) >> 1); return ((kk >> 3) * 4 + (c >> 5)) * 512 + ((kk & 7) * 32 + (c & 31)) * 2; }
; __device__ __forceinline__ int v_rd_base(int lane) { return ((lane & 3) << 3) | (((lane >> 2) & 3) << 6) | (((lane >> 4) & 1) << 5) | (((lane >> 5) & 1) << 8); }
; template <int OFF> __device__ __forceinline__ s16x4 tr_read(int vb) {
;   s16x4 r; asm volatile("ds_read_b64_tr_b16 %0, %1 offset:%2" : "=&v"(r) : "v"(vb), "i"(OFF) : "memory"); return r;
; }
; template <int D0> __device__ __forceinline__ void pv_one(f32x16& od, int vb, bf16x8 pa0, bf16x8 pa1, bf16x8 pa2, bf16x8 pa3) {
;   const s16x4 l0 = tr_read<v_rd_off(D0, 0, 0)>(vb), h0 = tr_read<v_rd_off(D0, 0, 1)>(vb), l1 = tr_read<v_rd_off(D0, 1, 0)>(vb), h1 = tr_read<v_rd_off(D0, 1, 1)>(vb);
;   const s16x4 l2 = tr_read<v_rd_off(D0, 2, 0)>(vb), h2 = tr_read<v_rd_off(D0, 2, 1)>(vb), l3 = tr_read<v_rd_off(D0, 3, 0)>(vb), h3 = tr_read<v_rd_off(D0, 3, 1)>(vb);
;   asm volatile("s_waitcnt lgkmcnt(0)" ::: "memory"); SBAR();
;     ...
;   od = __builtin_amdgcn_mfma_f32_32x32x16_bf16(pa0, PK(l0, h0), od, 0, 0, 0);
;   od = __builtin_amdgcn_mfma_f32_32x32x16_bf16(pa1, PK(l1, h1), od, 0, 0, 0);
;   od = __builtin_amdgcn_mfma_f32_32x32x16_bf16(pa2, PK(l2, h2), od, 0, 0, 0);
;   od = __builtin_amdgcn_mfma_f32_32x32x16_bf16(pa3, PK(l3, h3), od, 0, 0, 0);
;     ...
; }
; __device__ __forceinline__ void partialSM_fast(f32x16& p0, f32x16& p1) {
; #pragma unroll
;   for (int r = 0; r < 16; ++r) p0[r] = __builtin_amdgcn_exp2f(p0[r]);
; }
; __device__ __forceinline__ void finishSM_fast(f32x16& p0, f32x16& p1, float& l_reg, bf16x8& pa0, bf16x8& pa1, bf16x8& pa2, bf16x8& pa3) {
; #pragma unroll
;   for (int r = 0; r < 16; ++r) p1[r] = __builtin_amdgcn_exp2f(p1[r]);
;   float ps = 0;
	v_mfma_f32_32x32x16_bf16 v[96:111], v[160:163], v[128:131], v[96:111]
	ds_read_b128 v[160:163], v200 offset:8192
	v_cvt_pk_bf16_f32 v156, v72, v73
	v_cvt_pk_bf16_f32 v157, v74, v75
	v_add_f32_e32 v239, v73, v239
	v_add_f32_e32 v239, v74, v239
	v_mfma_f32_32x32x16_bf16 v[96:111], v[164:167], v[132:135], v[96:111]
	ds_read_b128 v[164:167], v201 offset:8192
	v_cvt_pk_bf16_f32 v158, v76, v77
	v_cvt_pk_bf16_f32 v159, v78, v79
	v_add_f32_e32 v239, v75, v239
	v_add_f32_e32 v239, v76, v239
	v_mfma_f32_32x32x16_bf16 v[96:111], v[168:171], v[136:139], v[96:111]
	ds_read_b128 v[168:171], v202 offset:8192
	v_add_f32_e32 v239, v77, v239
	v_add_f32_e32 v239, v78, v239
	v_mfma_f32_32x32x16_bf16 v[96:111], v[172:175], v[148:151], v[96:111]
	ds_read_b128 v[172:175], v203 offset:8192
	v_add_f32_e32 v239, v79, v239
	v_add_f32_e32 v197, v239, v197
	s_waitcnt lgkmcnt(4)
	v_mfma_f32_32x32x16_bf16 v[64:79], v[206:209], v[112:115], 0
	v_mfma_f32_32x32x16_bf16 v[64:79], v[210:213], v[116:119], v[64:79]
	v_mfma_f32_32x32x16_bf16 v[64:79], v[214:217], v[120:123], v[64:79]
	ds_read_b64_tr_b16 v[222:223], v188 offset:49152
	ds_read_b64_tr_b16 v[224:225], v188 offset:51200
	v_mfma_f32_32x32x16_bf16 v[64:79], v[218:221], v[124:127], v[64:79]
	ds_read_b64_tr_b16 v[226:227], v188 offset:49664
	ds_read_b64_tr_b16 v[228:229], v188 offset:51712
	v_exp_f32_e32 v96, v96
	v_exp_f32_e32 v97, v97
	s_waitcnt lgkmcnt(4)
	v_mfma_f32_32x32x16_bf16 v[64:79], v[160:163], v[128:131], v[64:79]
	ds_read_b64_tr_b16 v[230:231], v188 offset:50176
	ds_read_b64_tr_b16 v[232:233], v188 offset:52224
	v_exp_f32_e32 v98, v98
	v_exp_f32_e32 v99, v99
	v_exp_f32_e32 v100, v100
	v_mfma_f32_32x32x16_bf16 v[64:79], v[164:167], v[132:135], v[64:79]
	ds_read_b64_tr_b16 v[234:235], v188 offset:50688
	ds_read_b64_tr_b16 v[236:237], v188 offset:52736
	v_exp_f32_e32 v101, v101
	v_exp_f32_e32 v102, v102
	v_exp_f32_e32 v103, v103
	v_mfma_f32_32x32x16_bf16 v[64:79], v[168:171], v[136:139], v[64:79]
	ds_read_b64_tr_b16 v[240:241], v188 offset:53248
	ds_read_b64_tr_b16 v[242:243], v188 offset:55296
	v_exp_f32_e32 v104, v104
	v_exp_f32_e32 v105, v105
	v_mfma_f32_32x32x16_bf16 v[64:79], v[172:175], v[148:151], v[64:79]
	ds_read_b64_tr_b16 v[180:181], v188 offset:53760
	ds_read_b64_tr_b16 v[182:183], v188 offset:55808
	v_exp_f32_e32 v106, v106
	v_exp_f32_e32 v107, v107
	s_waitcnt lgkmcnt(6)
	v_mfma_f32_32x32x16_bf16 v[0:15], v[140:143], v[222:225], v[0:15]
	ds_read_b64_tr_b16 v[222:223], v188 offset:54272
	ds_read_b64_tr_b16 v[224:225], v188 offset:56320
	v_exp_f32_e32 v108, v108
	v_exp_f32_e32 v109, v109
	v_mfma_f32_32x32x16_bf16 v[16:31], v[140:143], v[226:229], v[16:31]
	ds_read_b64_tr_b16 v[226:227], v188 offset:54784
	ds_read_b64_tr_b16 v[228:229], v188 offset:56832
	v_exp_f32_e32 v110, v110
	v_exp_f32_e32 v111, v111
	v_mfma_f32_32x32x16_bf16 v[32:47], v[140:143], v[230:233], v[32:47]
	ds_read_b64_tr_b16 v[230:231], v188 offset:57344
	ds_read_b64_tr_b16 v[232:233], v188 offset:59392
	v_exp_f32_e32 v64, v64
	v_exp_f32_e32 v65, v65
	s_waitcnt lgkmcnt(6)
	v_mfma_f32_32x32x16_bf16 v[48:63], v[140:143], v[234:237], v[48:63]
	ds_read_b64_tr_b16 v[234:235], v188 offset:57856
	ds_read_b64_tr_b16 v[236:237], v188 offset:59904
	v_exp_f32_e32 v66, v66
	v_exp_f32_e32 v67, v67
	v_mfma_f32_32x32x16_bf16 v[0:15], v[144:147], v[240:243], v[0:15]
	ds_read_b64_tr_b16 v[240:241], v188 offset:58368
	ds_read_b64_tr_b16 v[242:243], v188 offset:60416
	v_exp_f32_e32 v68, v68
	v_exp_f32_e32 v69, v69
	v_cvt_pk_bf16_f32 v140, v96, v97
	v_cvt_pk_bf16_f32 v141, v98, v99
	v_mfma_f32_32x32x16_bf16 v[16:31], v[144:147], v[180:183], v[16:31]
	ds_read_b64_tr_b16 v[180:181], v188 offset:58880
	ds_read_b64_tr_b16 v[182:183], v188 offset:60928
	v_exp_f32_e32 v70, v70
	v_exp_f32_e32 v71, v71
	v_cvt_pk_bf16_f32 v142, v100, v101
	v_cvt_pk_bf16_f32 v143, v102, v103
	s_waitcnt lgkmcnt(6)
	v_mfma_f32_32x32x16_bf16 v[32:47], v[144:147], v[222:225], v[32:47]
	ds_read_b64_tr_b16 v[222:223], v188 offset:61440
	ds_read_b64_tr_b16 v[224:225], v188 offset:63488
	v_exp_f32_e32 v72, v72
	v_exp_f32_e32 v73, v73
	v_mfma_f32_32x32x16_bf16 v[48:63], v[144:147], v[226:229], v[48:63]
	ds_read_b64_tr_b16 v[226:227], v188 offset:61952
	ds_read_b64_tr_b16 v[228:229], v188 offset:64000
	v_exp_f32_e32 v74, v74
	v_exp_f32_e32 v75, v75
	v_mfma_f32_32x32x16_bf16 v[0:15], v[152:155], v[230:233], v[0:15]
	ds_read_b64_tr_b16 v[230:231], v188 offset:62464
	ds_read_b64_tr_b16 v[232:233], v188 offset:64512
	v_exp_f32_e32 v76, v76
	v_exp_f32_e32 v77, v77
	v_cvt_pk_bf16_f32 v144, v104, v105
	v_cvt_pk_bf16_f32 v145, v106, v107
	s_waitcnt lgkmcnt(6)
	v_mfma_f32_32x32x16_bf16 v[16:31], v[152:155], v[234:237], v[16:31]
	ds_read_b64_tr_b16 v[234:235], v188 offset:62976
	ds_read_b64_tr_b16 v[236:237], v188 offset:65024
	v_exp_f32_e32 v78, v78
	v_exp_f32_e32 v79, v79
	v_cvt_pk_bf16_f32 v146, v108, v109
	v_cvt_pk_bf16_f32 v147, v110, v111
	s_waitcnt vmcnt(6)
	s_barrier
; #define SBAR() __builtin_amdgcn_sched_barrier(0)
; #define SWAIT() asm volatile("s_waitcnt vmcnt(4)" ::: "memory")
; #define MASKLAST(P0, P1) do { _Pragma("unroll") for (int r = 8; r < 16; ++r) P0[r] = -1e30f; _Pragma("unroll") for (int r = 0; r < 16; ++r) P1[r] = -1e30f; } while (0)
; template <int D0> __device__ __forceinline__ void pv_one(f32x16& od, int vb, bf16x8 pa0, bf16x8 pa1, bf16x8 pa2, bf16x8 pa3) {
;   const s16x4 l0 = tr_read<v_rd_off(D0, 0, 0)>(vb), h0 = tr_read<v_rd_off(D0, 0, 1)>(vb), l1 = tr_read<v_rd_off(D0, 1, 0)>(vb), h1 = tr_read<v_rd_off(D0, 1, 1)>(vb);
;   const s16x4 l2 = tr_read<v_rd_off(D0, 2, 0)>(vb), h2 = tr_read<v_rd_off(D0, 2, 1)>(vb), l3 = tr_read<v_rd_off(D0, 3, 0)>(vb), h3 = tr_read<v_rd_off(D0, 3, 1)>(vb);
;   asm volatile("s_waitcnt lgkmcnt(0)" ::: "memory"); SBAR();
;     ...
;   od = __builtin_amdgcn_mfma_f32_32x32x16_bf16(pa0, PK(l0, h0), od, 0, 0, 0);
;   od = __builtin_amdgcn_mfma_f32_32x32x16_bf16(pa1, PK(l1, h1), od, 0, 0, 0);
;   od = __builtin_amdgcn_mfma_f32_32x32x16_bf16(pa2, PK(l2, h2), od, 0, 0, 0);
;   od = __builtin_amdgcn_mfma_f32_32x32x16_bf16(pa3, PK(l3, h3), od, 0, 0, 0);
;     ...
; }
; __device__ __forceinline__ void attn_unit_fast(const bf16* __restrict__ Qb, const bf16* __restrict__ Kh, const bf16* __restrict__ Vh, bf16* __restrict__ Ob, int NT, char* lds, int t0, const float* __restrict__ qg) {
;     ...
;   for (int j = 1; j + 1 < NT; j += 2) {
;     SBAR(); qkt(pB0, pB1, (bf16*)((char*)K_lds + SHM_K), qr, r32, hi);
;     finishSM_fast(pA0, pA1, l_reg, pa0, pa1, pa2, pa3); SBAR();
;     if (j + 2 < NT) SLOAD(SO, (j + 2) * KVBLK); SBAR();
;     pv_d0(o, vb0, pa0, pa1, pa2, pa3); partialSM_fast(pB0, pB1);
;     __syncthreads(); SWAIT(); SWRITE(0, SE);
;     __syncthreads();
;     SBAR(); qkt(pA0, pA1, K_lds, qr, r32, hi);
;     if (j + 2 == NT) MASKLAST(pA0, pA1);
;     finishSM_fast(pB0, pB1, l_reg, pa0, pa1, pa2, pa3); SBAR();
;     if (j + 3 < NT) SLOAD(SE, (j + 3) * KVBLK); SBAR();
;     pv_d0(o, vb0 + (int)SHM_V, pa0, pa1, pa2, pa3); partialSM_fast(pA0, pA1);
;     __syncthreads(); SWAIT(); SWRITE(1, SO);
;     __syncthreads();
;   }
;   finishSM_fast(pA0, pA1, l_reg, pa0, pa1, pa2, pa3); SBAR();
;   pv_d0(o, vb0, pa0, pa1, pa2, pa3);
;   { int r32e = r32; asm volatile("" : "+v"(r32e)); if (hi == 0) li_l[r32e] = l_reg; }
;   asm volatile("s_waitcnt lgkmcnt(0)" ::: "memory");
	v_mfma_f32_32x32x16_bf16 v[32:47], v[152:155], v[240:243], v[32:47]
	s_add_u32 m0, s5, 0x8000
	v_add_f32_e32 v238, v96, v97
	global_load_lds_dwordx4 v253, s[0:1]
	v_add_f32_e32 v238, v98, v238
	v_add_f32_e32 v238, v99, v238
	v_mfma_f32_32x32x16_bf16 v[48:63], v[152:155], v[180:183], v[48:63]
	s_add_u32 m0, s5, 0xa000
	v_add_f32_e32 v238, v100, v238
	global_load_lds_dwordx4 v254, s[0:1]
	v_add_f32_e32 v238, v101, v238
	v_add_f32_e32 v238, v102, v238
	s_add_u32 s0, s0, 0x4000
	s_addc_u32 s1, s1, 0
	s_waitcnt lgkmcnt(2)
	v_mfma_f32_32x32x16_bf16 v[0:15], v[156:159], v[222:225], v[0:15]
	v_add_f32_e32 v238, v103, v238
	v_add_f32_e32 v238, v104, v238
	v_add_f32_e32 v238, v105, v238
	ds_read_b128 v[206:209], v194 offset:16384
	ds_read_b128 v[210:213], v196 offset:16384
	v_mfma_f32_32x32x16_bf16 v[16:31], v[156:159], v[226:229], v[16:31]
	v_add_f32_e32 v238, v106, v238
	v_add_f32_e32 v238, v107, v238
	v_add_f32_e32 v238, v108, v238
	ds_read_b128 v[214:217], v198 offset:16384
	ds_read_b128 v[218:221], v199 offset:16384
	v_mfma_f32_32x32x16_bf16 v[32:47], v[156:159], v[230:233], v[32:47]
	v_add_f32_e32 v238, v109, v238
	v_add_f32_e32 v238, v110, v238
	ds_read_b128 v[160:163], v200 offset:16384
	ds_read_b128 v[164:167], v201 offset:16384
	s_waitcnt lgkmcnt(6)
	v_mfma_f32_32x32x16_bf16 v[48:63], v[156:159], v[234:237], v[48:63]
	v_add_f32_e32 v238, v111, v238
	v_add_f32_e32 v197, v238, v197
	ds_read_b128 v[168:171], v202 offset:16384
	ds_read_b128 v[172:175], v203 offset:16384
	s_sub_u32 s4, s4, 1
	s_cmp_lg_u32 s4, 0
	s_cbranch_scc1 .Lattn_loop
	v_cvt_pk_bf16_f32 v152, v64, v65
	v_cvt_pk_bf16_f32 v153, v66, v67
	v_cvt_pk_bf16_f32 v154, v68, v69
	v_cvt_pk_bf16_f32 v155, v70, v71
	v_cvt_pk_bf16_f32 v156, v72, v73
	v_cvt_pk_bf16_f32 v157, v74, v75
	v_cvt_pk_bf16_f32 v158, v76, v77
	v_cvt_pk_bf16_f32 v159, v78, v79
	v_add_f32_e32 v239, v64, v65
	v_add_f32_e32 v239, v66, v239
	v_add_f32_e32 v239, v67, v239
	v_add_f32_e32 v239, v68, v239
	v_add_f32_e32 v239, v69, v239
	v_add_f32_e32 v239, v70, v239
	v_add_f32_e32 v239, v71, v239
	v_add_f32_e32 v239, v72, v239
	v_add_f32_e32 v239, v73, v239
	v_add_f32_e32 v239, v74, v239
	v_add_f32_e32 v239, v75, v239
	v_add_f32_e32 v239, v76, v239
	v_add_f32_e32 v239, v77, v239
	v_add_f32_e32 v239, v78, v239
	v_add_f32_e32 v239, v79, v239
	v_add_f32_e32 v197, v239, v197
	s_waitcnt lgkmcnt(0)
	ds_read_b64_tr_b16 v[222:223], v188
	ds_read_b64_tr_b16 v[224:225], v188 offset:2048
	ds_read_b64_tr_b16 v[226:227], v188 offset:512
	ds_read_b64_tr_b16 v[228:229], v188 offset:2560
	ds_read_b64_tr_b16 v[230:231], v188 offset:1024
	ds_read_b64_tr_b16 v[232:233], v188 offset:3072
	ds_read_b64_tr_b16 v[234:235], v188 offset:1536
	ds_read_b64_tr_b16 v[236:237], v188 offset:3584
	ds_read_b64_tr_b16 v[240:241], v188 offset:4096
	ds_read_b64_tr_b16 v[242:243], v188 offset:6144
	ds_read_b64_tr_b16 v[180:181], v188 offset:4608
	ds_read_b64_tr_b16 v[182:183], v188 offset:6656
	s_waitcnt lgkmcnt(6)
	v_mfma_f32_32x32x16_bf16 v[0:15], v[140:143], v[222:225], v[0:15]
	ds_read_b64_tr_b16 v[222:223], v188 offset:5120
	ds_read_b64_tr_b16 v[224:225], v188 offset:7168
	v_mfma_f32_32x32x16_bf16 v[16:31], v[140:143], v[226:229], v[16:31]
	ds_read_b64_tr_b16 v[226:227], v188 offset:5632
	ds_read_b64_tr_b16 v[228:229], v188 offset:7680
	v_mfma_f32_32x32x16_bf16 v[32:47], v[140:143], v[230:233], v[32:47]
	ds_read_b64_tr_b16 v[230:231], v188 offset:8192
	ds_read_b64_tr_b16 v[232:233], v188 offset:10240
	s_waitcnt lgkmcnt(6)
	v_mfma_f32_32x32x16_bf16 v[48:63], v[140:143], v[234:237], v[48:63]
	ds_read_b64_tr_b16 v[234:235], v188 offset:8704
	ds_read_b64_tr_b16 v[236:237], v188 offset:10752
	v_mfma_f32_32x32x16_bf16 v[0:15], v[144:147], v[240:243], v[0:15]
	ds_read_b64_tr_b16 v[240:241], v188 offset:9216
	ds_read_b64_tr_b16 v[242:243], v188 offset:11264
	v_mfma_f32_32x32x16_bf16 v[16:31], v[144:147], v[180:183], v[16:31]
	ds_read_b64_tr_b16 v[180:181], v188 offset:9728
	ds_read_b64_tr_b16 v[182:183], v188 offset:11776
	s_waitcnt lgkmcnt(6)
	v_mfma_f32_32x32x16_bf16 v[32:47], v[144:147], v[222:225], v[32:47]
	ds_read_b64_tr_b16 v[222:223], v188 offset:12288
	ds_read_b64_tr_b16 v[224:225], v188 offset:14336
	v_mfma_f32_32x32x16_bf16 v[48:63], v[144:147], v[226:229], v[48:63]
	ds_read_b64_tr_b16 v[226:227], v188 offset:12800
	ds_read_b64_tr_b16 v[228:229], v188 offset:14848
	v_mfma_f32_32x32x16_bf16 v[0:15], v[152:155], v[230:233], v[0:15]
	ds_read_b64_tr_b16 v[230:231], v188 offset:13312
	ds_read_b64_tr_b16 v[232:233], v188 offset:15360
	s_waitcnt lgkmcnt(6)
	v_mfma_f32_32x32x16_bf16 v[16:31], v[152:155], v[234:237], v[16:31]
	ds_read_b64_tr_b16 v[234:235], v188 offset:13824
	ds_read_b64_tr_b16 v[236:237], v188 offset:15872
	v_mfma_f32_32x32x16_bf16 v[32:47], v[152:155], v[240:243], v[32:47]
	v_mfma_f32_32x32x16_bf16 v[48:63], v[152:155], v[180:183], v[48:63]
	s_waitcnt lgkmcnt(2)
	v_mfma_f32_32x32x16_bf16 v[0:15], v[156:159], v[222:225], v[0:15]
	v_mfma_f32_32x32x16_bf16 v[16:31], v[156:159], v[226:229], v[16:31]
	v_mfma_f32_32x32x16_bf16 v[32:47], v[156:159], v[230:233], v[32:47]
	s_waitcnt lgkmcnt(0)
	v_mfma_f32_32x32x16_bf16 v[48:63], v[156:159], v[234:237], v[48:63]
	s_waitcnt vmcnt(0)
	v_mov_b32_e32 v64, v197
	v_mov_b32_e32 v65, v197
	v_and_b32_e32 v80, 0x3fffffc0, v195
	s_mov_b32 s0, 0x10000
	v_permlane32_swap_b32_e32 v64, v65
	v_lshl_add_u32 v80, v80, 2, s0
	v_cmp_gt_u32_e32 vcc, 32, v179
	v_add_f32_e32 v64, v64, v65
	v_mov_b32_e32 v66, v191
	v_add_f32_e32 v64, 0xc2400000, v64
	s_nop 3
	s_and_saveexec_b64 s[0:1], vcc
	s_cbranch_execz .LBB0_439
	v_lshl_add_u32 v65, v66, 2, v80
	ds_write_b32 v65, v64
	s_branch .LBB0_439
